# nt hint also on the attention q and z_attn read-once loads (on top of P0 x-load nt)
# baseline (speedup 1.0000x reference)
; __device__ __forceinline__ int lane_id_asm() { int r; asm volatile("v_mbcnt_lo_u32_b32 %0, -1, 0\n\tv_mbcnt_hi_u32_b32 %0, -1, %0" : "=v"(r)); return r; }
; __device__ __forceinline__ bf16_t f2bf(float f) { return (bf16_t)(cvtpk(f, f) & 0xffffu); }
; __device__ __forceinline__ int crow(int r, int hi) { return (r & 3) + 8 * (r >> 2) + 4 * hi; }
; __device__ __forceinline__ void attn_item(const bf16_t* __restrict__ Qb, const bf16_t* __restrict__ Kh, const bf16_t* __restrict__ Vh, const bf16_t* __restrict__ Zb, ...
;     ...
;   const int lane_e = lane_id_asm(), r32e = lane_e & 31, hie = lane_e >> 5;
;   float* li_e = (float*)(lds + 3 * 32768) + wid_s * 64;
;   { auto rr = __builtin_amdgcn_permlane32_swap(__float_as_uint(l_reg), __float_as_uint(l_reg), false, false); l_reg = __uint_as_float(rr[0]) + __uint_as_float(rr[1]); }
;   if (hie == 0) li_e[r32e] = l_reg; asm volatile("s_waitcnt lgkmcnt(0)" ::: "memory");
;   float rli[16];
; #pragma unroll
;   for (int r = 0; r < 16; ++r) rli[r] = __builtin_amdgcn_rcpf(li_e[crow(r, hie)]);
;   bf16_t* Ow = Ob + (long)(wid_s * QBLK) * LDAF; const bf16_t* Zw = Zb + (long)(wid_s * QBLK) * LDP;
;   bf16_t* stg = (bf16_t*)lds + wid_s * 4096;
; #pragma unroll
;   for (int r = 0; r < 16; ++r) { const int orow = crow(r, hie);
; #pragma unroll
;     for (int d0 = 0; d0 < 4; ++d0) stg[orow * 128 + d0 * 32 + r32e] = f2bf(o[d0][r] * rli[r]); }
.LBB0_451:
	s_or_b64 exec, exec, s[0:1]
	v_ashrrev_i32_e32 v66, 5, v0
	s_waitcnt lgkmcnt(0)
	v_lshl_add_u32 v76, v66, 4, s38
	ds_read_b128 v[68:71], v76
	ds_read_b128 v[72:75], v76 offset:32
	v_lshlrev_b32_e32 v66, 10, v66
	v_lshlrev_b32_e32 v67, 1, v67
	v_add3_u32 v66, s53, v66, v67
	s_waitcnt lgkmcnt(1)
	v_rcp_f32_e32 v77, v68
	v_rcp_f32_e32 v78, v69
	v_rcp_f32_e32 v79, v70
	v_rcp_f32_e32 v80, v71
	v_mul_f32_e32 v50, v50, v77
	v_mul_f32_e32 v34, v34, v77
	v_mul_f32_e32 v18, v18, v77
	v_mul_f32_e32 v2, v2, v77
	s_waitcnt lgkmcnt(0)
	v_rcp_f32_e32 v81, v72
	ds_read_b128 v[68:71], v76 offset:64
	v_rcp_f32_e32 v82, v73
	v_rcp_f32_e32 v83, v74
	v_rcp_f32_e32 v84, v75
	ds_read_b128 v[72:75], v76 offset:96
	v_cvt_pk_bf16_f32 v50, v50, v50
	ds_write_b16 v66, v50
	v_cvt_pk_bf16_f32 v34, v34, v34
	ds_write_b16 v66, v34 offset:64
	v_cvt_pk_bf16_f32 v18, v18, v18
	ds_write_b16 v66, v18 offset:128
	v_cvt_pk_bf16_f32 v2, v2, v2
	ds_write_b16 v66, v2 offset:192
	v_mul_f32_e32 v2, v51, v78
	v_cvt_pk_bf16_f32 v2, v2, v2
	ds_write_b16 v66, v2 offset:256
	v_mul_f32_e32 v2, v35, v78
	v_cvt_pk_bf16_f32 v2, v2, v2
	ds_write_b16 v66, v2 offset:320
	v_mul_f32_e32 v2, v19, v78
	v_cvt_pk_bf16_f32 v2, v2, v2
	ds_write_b16 v66, v2 offset:384
	v_mul_f32_e32 v2, v3, v78
	v_cvt_pk_bf16_f32 v2, v2, v2
	ds_write_b16 v66, v2 offset:448
	v_mul_f32_e32 v2, v52, v79
	v_cvt_pk_bf16_f32 v2, v2, v2
	ds_write_b16 v66, v2 offset:512
	v_mul_f32_e32 v2, v36, v79
	v_cvt_pk_bf16_f32 v2, v2, v2
	ds_write_b16 v66, v2 offset:576
	v_mul_f32_e32 v2, v20, v79
	v_cvt_pk_bf16_f32 v2, v2, v2
	ds_write_b16 v66, v2 offset:640
	v_mul_f32_e32 v2, v4, v79
	v_cvt_pk_bf16_f32 v2, v2, v2
	ds_write_b16 v66, v2 offset:704
	v_mul_f32_e32 v2, v53, v80
	v_cvt_pk_bf16_f32 v2, v2, v2
	ds_write_b16 v66, v2 offset:768
	v_mul_f32_e32 v2, v37, v80
	v_cvt_pk_bf16_f32 v2, v2, v2
	ds_write_b16 v66, v2 offset:832
	v_mul_f32_e32 v2, v21, v80
	v_cvt_pk_bf16_f32 v2, v2, v2
	ds_write_b16 v66, v2 offset:896
	v_mul_f32_e32 v2, v5, v80
	v_cvt_pk_bf16_f32 v2, v2, v2
	ds_write_b16 v66, v2 offset:960
	v_mul_f32_e32 v2, v54, v81
	v_cvt_pk_bf16_f32 v2, v2, v2
	ds_write_b16 v66, v2 offset:2048
	v_mul_f32_e32 v2, v38, v81
	v_cvt_pk_bf16_f32 v2, v2, v2
	ds_write_b16 v66, v2 offset:2112
	v_mul_f32_e32 v2, v22, v81
	v_cvt_pk_bf16_f32 v2, v2, v2
	ds_write_b16 v66, v2 offset:2176
	v_mul_f32_e32 v2, v6, v81
	v_cvt_pk_bf16_f32 v2, v2, v2
	ds_write_b16 v66, v2 offset:2240
	v_mul_f32_e32 v2, v55, v82
	v_cvt_pk_bf16_f32 v2, v2, v2
	ds_write_b16 v66, v2 offset:2304
	v_mul_f32_e32 v2, v39, v82
	v_cvt_pk_bf16_f32 v2, v2, v2
	ds_write_b16 v66, v2 offset:2368
	v_mul_f32_e32 v2, v23, v82
	v_cvt_pk_bf16_f32 v2, v2, v2
	ds_write_b16 v66, v2 offset:2432
	v_mul_f32_e32 v2, v7, v82
	v_cvt_pk_bf16_f32 v2, v2, v2
	ds_write_b16 v66, v2 offset:2496
	v_mul_f32_e32 v2, v56, v83
	v_cvt_pk_bf16_f32 v2, v2, v2
	ds_write_b16 v66, v2 offset:2560
	v_mul_f32_e32 v2, v40, v83
	v_cvt_pk_bf16_f32 v2, v2, v2
	ds_write_b16 v66, v2 offset:2624
	v_mul_f32_e32 v2, v24, v83
	v_cvt_pk_bf16_f32 v2, v2, v2
	ds_write_b16 v66, v2 offset:2688
	v_mul_f32_e32 v2, v8, v83
	v_cvt_pk_bf16_f32 v2, v2, v2
	ds_write_b16 v66, v2 offset:2752
	v_mul_f32_e32 v2, v57, v84
	v_cvt_pk_bf16_f32 v2, v2, v2
	ds_write_b16 v66, v2 offset:2816
	v_mul_f32_e32 v2, v41, v84
	v_cvt_pk_bf16_f32 v2, v2, v2
	s_waitcnt lgkmcnt(14)
	v_rcp_f32_e32 v68, v68
	ds_write_b16 v66, v2 offset:2880
	v_mul_f32_e32 v2, v25, v84
	v_cvt_pk_bf16_f32 v2, v2, v2
	ds_write_b16 v66, v2 offset:2944
	v_mul_f32_e32 v2, v9, v84
	v_cvt_pk_bf16_f32 v2, v2, v2
	ds_write_b16 v66, v2 offset:3008
	v_mul_f32_e32 v2, v58, v68
	v_cvt_pk_bf16_f32 v2, v2, v2
	ds_write_b16 v66, v2 offset:4096
	v_mul_f32_e32 v2, v42, v68
	v_cvt_pk_bf16_f32 v2, v2, v2
	v_rcp_f32_e32 v69, v69
	ds_write_b16 v66, v2 offset:4160
	v_mul_f32_e32 v2, v26, v68
	v_cvt_pk_bf16_f32 v2, v2, v2
	ds_write_b16 v66, v2 offset:4224
	v_mul_f32_e32 v2, v10, v68
	v_cvt_pk_bf16_f32 v2, v2, v2
	ds_write_b16 v66, v2 offset:4288
	v_mul_f32_e32 v2, v59, v69
	v_cvt_pk_bf16_f32 v2, v2, v2
	ds_write_b16 v66, v2 offset:4352
	v_mul_f32_e32 v2, v43, v69
	v_cvt_pk_bf16_f32 v2, v2, v2
	v_rcp_f32_e32 v70, v70
	ds_write_b16 v66, v2 offset:4416
	v_mul_f32_e32 v2, v27, v69
	v_cvt_pk_bf16_f32 v2, v2, v2
	ds_write_b16 v66, v2 offset:4480
	v_mul_f32_e32 v2, v11, v69
	v_cvt_pk_bf16_f32 v2, v2, v2
	ds_write_b16 v66, v2 offset:4544
	v_mul_f32_e32 v2, v60, v70
	v_cvt_pk_bf16_f32 v2, v2, v2
	ds_write_b16 v66, v2 offset:4608
	v_mul_f32_e32 v2, v44, v70
	v_cvt_pk_bf16_f32 v2, v2, v2
	v_rcp_f32_e32 v71, v71
	ds_write_b16 v66, v2 offset:4672
	v_mul_f32_e32 v2, v28, v70
	v_cvt_pk_bf16_f32 v2, v2, v2
	ds_write_b16 v66, v2 offset:4736
	v_mul_f32_e32 v2, v12, v70
	v_cvt_pk_bf16_f32 v2, v2, v2
	ds_write_b16 v66, v2 offset:4800
	v_mul_f32_e32 v2, v61, v71
	v_cvt_pk_bf16_f32 v2, v2, v2
	ds_write_b16 v66, v2 offset:4864
	v_mul_f32_e32 v2, v45, v71
	v_cvt_pk_bf16_f32 v2, v2, v2
	v_rcp_f32_e32 v72, v72
	ds_write_b16 v66, v2 offset:4928
	v_mul_f32_e32 v2, v29, v71
	v_cvt_pk_bf16_f32 v2, v2, v2
	ds_write_b16 v66, v2 offset:4992
	v_mul_f32_e32 v2, v13, v71
	v_cvt_pk_bf16_f32 v2, v2, v2
	ds_write_b16 v66, v2 offset:5056
	v_mul_f32_e32 v2, v62, v72
	v_cvt_pk_bf16_f32 v2, v2, v2
	ds_write_b16 v66, v2 offset:6144
	v_mul_f32_e32 v2, v46, v72
	v_cvt_pk_bf16_f32 v2, v2, v2
	v_rcp_f32_e32 v73, v73
	ds_write_b16 v66, v2 offset:6208
	v_mul_f32_e32 v2, v30, v72
	v_cvt_pk_bf16_f32 v2, v2, v2
	ds_write_b16 v66, v2 offset:6272
	v_mul_f32_e32 v2, v14, v72
	v_cvt_pk_bf16_f32 v2, v2, v2
	ds_write_b16 v66, v2 offset:6336
	v_mul_f32_e32 v2, v63, v73
	v_cvt_pk_bf16_f32 v2, v2, v2
	ds_write_b16 v66, v2 offset:6400
	v_mul_f32_e32 v2, v47, v73
	v_cvt_pk_bf16_f32 v2, v2, v2
	v_rcp_f32_e32 v74, v74
	ds_write_b16 v66, v2 offset:6464
	v_mul_f32_e32 v2, v31, v73
	v_cvt_pk_bf16_f32 v2, v2, v2
	ds_write_b16 v66, v2 offset:6528
	v_mul_f32_e32 v2, v15, v73
	v_cvt_pk_bf16_f32 v2, v2, v2
	ds_write_b16 v66, v2 offset:6592
	v_mul_f32_e32 v2, v64, v74
	v_cvt_pk_bf16_f32 v2, v2, v2
	ds_write_b16 v66, v2 offset:6656
	v_mul_f32_e32 v2, v48, v74
	v_cvt_pk_bf16_f32 v2, v2, v2
	v_rcp_f32_e32 v75, v75
	ds_write_b16 v66, v2 offset:6720
	v_mul_f32_e32 v2, v32, v74
	v_cvt_pk_bf16_f32 v2, v2, v2
	s_mulk_i32 s71, 0xc00
	ds_write_b16 v66, v2 offset:6784
	v_mul_f32_e32 v2, v16, v74
	s_add_u32 s0, s74, s71
	v_cvt_pk_bf16_f32 v2, v2, v2
	s_addc_u32 s1, s75, 0
	ds_write_b16 v66, v2 offset:6848
	v_mul_f32_e32 v2, v65, v75
	s_add_u32 s0, s0, s26
	v_cvt_pk_bf16_f32 v2, v2, v2
	s_addc_u32 s1, s1, s27
	ds_write_b16 v66, v2 offset:6912
	v_mul_f32_e32 v2, v49, v75
	v_cvt_pk_bf16_f32 v2, v2, v2
	s_add_u32 s0, s0, s39
	ds_write_b16 v66, v2 offset:6976
	v_mul_f32_e32 v2, v33, v75
	s_addc_u32 s1, s1, s49
	v_cvt_pk_bf16_f32 v2, v2, v2
	s_add_u32 s6, s24, s50
	v_ashrrev_i32_e32 v22, 4, v0
	v_lshlrev_b32_e32 v0, 4, v0
	ds_write_b16 v66, v2 offset:7040
	v_mul_f32_e32 v2, v17, v75
	s_addc_u32 s7, s25, s52
	v_and_b32_e32 v0, 0xf0, v0
	v_cvt_pk_bf16_f32 v2, v2, v2
	ds_write_b16 v66, v2 offset:7104
	v_lshl_add_u64 v[4:5], s[6:7], 0, v[0:1]
	s_waitcnt lgkmcnt(0)
; __device__ __forceinline__ unsigned cvtpk(float lo, float hi) { unsigned r; asm volatile("v_cvt_pk_bf16_f32 %0, %1, %2" : "=v"(r) : "v"(lo), "v"(hi)); return r; }
; __device__ __forceinline__ float bflo(unsigned w) { return __uint_as_float(w << 16); }
; __device__ __forceinline__ float bfhi(unsigned w) { return __uint_as_float(w & 0xffff0000u); }
; __device__ __forceinline__ void attn_item(const bf16_t* __restrict__ Qb, const bf16_t* __restrict__ Kh, const bf16_t* __restrict__ Vh, const bf16_t* __restrict__ Zb, ...
;     ...
; #pragma unroll
;   for (int i = 0; i < 8; ++i) { const int row = i * 4 + (lane_e >> 4), ch = lane_e & 15;
;     const u32x4 ov = *(const u32x4*)(stg + row * 128 + ch * 8); const u32x4 zv = *(const u32x4*)(Zw + (long)row * LDP + ch * 8);
;     u32x4 w; w.x = cvtpk(bflo(ov.x) * bflo(zv.x), bfhi(ov.x) * bfhi(zv.x)); w.y = cvtpk(bflo(ov.y) * bflo(zv.y), bfhi(ov.y) * bfhi(zv.y));
;     w.z = cvtpk(bflo(ov.z) * bflo(zv.z), bfhi(ov.z) * bfhi(zv.z)); w.w = cvtpk(bflo(ov.w) * bflo(zv.w), bfhi(ov.w) * bfhi(zv.w));
;     *(u32x4*)(Ow + (long)row * LDAF + ch * 8) = w; }
	v_mad_i64_i32 v[2:3], s[6:7], v22, s51, v[4:5]
	global_load_dwordx4 v[6:9], v[2:3], off offset:3072 nt
	v_add_u32_e32 v23, s53, v0
	v_lshl_add_u32 v2, v22, 8, v23
	ds_read_b128 v[10:13], v2
	v_add_u32_e32 v20, 4, v22
	v_add_u32_e32 v24, 12, v22
	v_add_u32_e32 v25, 16, v22
	s_add_i32 s70, s70, s34
	s_waitcnt lgkmcnt(0)
	v_lshlrev_b32_e32 v2, 16, v10
	s_add_i32 s54, s54, s55
	s_cmpk_gt_i32 s70, 0x3ff
	s_waitcnt vmcnt(0)
	v_lshlrev_b32_e32 v3, 16, v6
	v_mul_f32_e32 v2, v3, v2
	v_and_b32_e32 v3, 0xffff0000, v6
	v_and_b32_e32 v6, 0xffff0000, v10
	v_mul_f32_e32 v3, v3, v6
	v_cvt_pk_bf16_f32 v6, v2, v3
	v_lshlrev_b32_e32 v2, 16, v11
	v_lshlrev_b32_e32 v3, 16, v7
	v_mul_f32_e32 v2, v3, v2
	v_and_b32_e32 v3, 0xffff0000, v7
	v_and_b32_e32 v7, 0xffff0000, v11
	v_mul_f32_e32 v3, v3, v7
	v_cvt_pk_bf16_f32 v7, v2, v3
	v_lshlrev_b32_e32 v2, 16, v12
	v_lshlrev_b32_e32 v3, 16, v8
	v_mul_f32_e32 v2, v3, v2
	v_and_b32_e32 v3, 0xffff0000, v8
	v_and_b32_e32 v8, 0xffff0000, v12
	v_mul_f32_e32 v3, v3, v8
	v_cvt_pk_bf16_f32 v8, v2, v3
	v_lshlrev_b32_e32 v2, 16, v13
	v_lshlrev_b32_e32 v3, 16, v9
	v_mul_f32_e32 v2, v3, v2
	v_and_b32_e32 v3, 0xffff0000, v9
	v_and_b32_e32 v9, 0xffff0000, v13
	v_mul_f32_e32 v3, v3, v9
	v_cvt_pk_bf16_f32 v9, v2, v3
	v_mad_i64_i32 v[2:3], s[6:7], v20, s51, v[4:5]
	global_load_dwordx4 v[10:13], v[2:3], off offset:3072 nt
	v_lshl_add_u32 v2, v20, 8, v23
	ds_read_b128 v[14:17], v2
	v_lshl_add_u64 v[2:3], s[0:1], 0, v[0:1]
	v_mad_i64_i32 v[18:19], s[0:1], v22, s48, v[2:3]
	global_store_dwordx4 v[18:19], v[6:9], off
	s_waitcnt lgkmcnt(0)
	v_lshlrev_b32_e32 v0, 16, v14
	v_mad_i64_i32 v[18:19], s[0:1], v20, s48, v[2:3]
	v_and_b32_e32 v7, 0xffff0000, v14
	v_and_b32_e32 v8, 0xffff0000, v15
	v_and_b32_e32 v9, 0xffff0000, v16
	v_mad_i64_i32 v[20:21], s[0:1], v25, s51, v[4:5]
	s_waitcnt vmcnt(1)
	v_lshlrev_b32_e32 v6, 16, v10
	v_mul_f32_e32 v0, v6, v0
	v_and_b32_e32 v6, 0xffff0000, v10
	v_mul_f32_e32 v6, v6, v7
	v_cvt_pk_bf16_f32 v6, v0, v6
	v_lshlrev_b32_e32 v0, 16, v15
	v_lshlrev_b32_e32 v7, 16, v11
	v_mul_f32_e32 v0, v7, v0
	v_and_b32_e32 v7, 0xffff0000, v11
	v_mul_f32_e32 v7, v7, v8
	v_cvt_pk_bf16_f32 v7, v0, v7
	v_lshlrev_b32_e32 v0, 16, v16
	v_lshlrev_b32_e32 v8, 16, v12
	v_mul_f32_e32 v0, v8, v0
	v_and_b32_e32 v8, 0xffff0000, v12
	v_mul_f32_e32 v8, v8, v9
	v_cvt_pk_bf16_f32 v8, v0, v8
	v_lshlrev_b32_e32 v0, 16, v17
	v_lshlrev_b32_e32 v9, 16, v13
	v_mul_f32_e32 v0, v9, v0
	v_and_b32_e32 v9, 0xffff0000, v13
	v_and_b32_e32 v10, 0xffff0000, v17
	v_mul_f32_e32 v9, v9, v10
	v_cvt_pk_bf16_f32 v9, v0, v9
	v_add_u32_e32 v0, 8, v22
	v_mad_i64_i32 v[10:11], s[0:1], v0, s51, v[4:5]
	global_load_dwordx4 v[10:13], v[10:11], off offset:3072 nt
	v_lshl_add_u32 v14, v0, 8, v23
	ds_read_b128 v[14:17], v14
	global_store_dwordx4 v[18:19], v[6:9], off
	v_mad_i64_i32 v[18:19], s[0:1], v0, s48, v[2:3]
	s_waitcnt lgkmcnt(0)
	v_lshlrev_b32_e32 v6, 16, v14
	v_and_b32_e32 v7, 0xffff0000, v14
	v_lshlrev_b32_e32 v8, 16, v15
	v_and_b32_e32 v9, 0xffff0000, v15
	s_waitcnt vmcnt(1)
	v_lshlrev_b32_e32 v14, 16, v10
	v_and_b32_e32 v10, 0xffff0000, v10
	v_lshlrev_b32_e32 v15, 16, v11
	v_and_b32_e32 v11, 0xffff0000, v11
	v_mul_f32_e32 v6, v14, v6
	v_mul_f32_e32 v7, v10, v7
	v_mul_f32_e32 v8, v15, v8
	v_cvt_pk_bf16_f32 v6, v6, v7
	v_mul_f32_e32 v7, v11, v9
	v_cvt_pk_bf16_f32 v7, v8, v7
	v_lshlrev_b32_e32 v8, 16, v16
	v_lshlrev_b32_e32 v9, 16, v12
	v_mul_f32_e32 v8, v9, v8
	v_and_b32_e32 v9, 0xffff0000, v12
	v_and_b32_e32 v10, 0xffff0000, v16
	v_mul_f32_e32 v9, v9, v10
	v_cvt_pk_bf16_f32 v8, v8, v9
	v_lshlrev_b32_e32 v9, 16, v17
	v_lshlrev_b32_e32 v10, 16, v13
	v_mul_f32_e32 v9, v10, v9
	v_and_b32_e32 v10, 0xffff0000, v13
	v_and_b32_e32 v11, 0xffff0000, v17
	v_mul_f32_e32 v10, v10, v11
	v_cvt_pk_bf16_f32 v9, v9, v10
	v_mad_i64_i32 v[10:11], s[0:1], v24, s51, v[4:5]
	global_load_dwordx4 v[10:13], v[10:11], off offset:3072 nt
	v_lshl_add_u32 v14, v24, 8, v23
	ds_read_b128 v[14:17], v14
	global_store_dwordx4 v[18:19], v[6:9], off
	s_waitcnt lgkmcnt(0)
	v_lshlrev_b32_e32 v0, 16, v14
	v_and_b32_e32 v6, 0xffff0000, v14
	v_lshlrev_b32_e32 v7, 16, v15
	v_and_b32_e32 v8, 0xffff0000, v15
	v_lshlrev_b32_e32 v9, 16, v16
	v_and_b32_e32 v14, 0xffff0000, v16
	v_lshlrev_b32_e32 v15, 16, v17
	v_and_b32_e32 v16, 0xffff0000, v17
	s_waitcnt vmcnt(1)
	v_lshlrev_b32_e32 v17, 16, v10
	v_and_b32_e32 v10, 0xffff0000, v10
	v_lshlrev_b32_e32 v18, 16, v11
	v_and_b32_e32 v11, 0xffff0000, v11
	v_lshlrev_b32_e32 v19, 16, v12
	v_and_b32_e32 v12, 0xffff0000, v12
	v_lshlrev_b32_e32 v26, 16, v13
	v_and_b32_e32 v13, 0xffff0000, v13
	v_mul_f32_e32 v6, v10, v6
	v_mul_f32_e32 v7, v18, v7
	v_mul_f32_e32 v8, v11, v8
	v_mul_f32_e32 v9, v19, v9
	v_mul_f32_e32 v10, v12, v14
	v_mul_f32_e32 v11, v26, v15
	v_mul_f32_e32 v12, v13, v16
	v_mul_f32_e32 v0, v17, v0
	v_cvt_pk_bf16_f32 v6, v0, v6
	v_cvt_pk_bf16_f32 v7, v7, v8
	v_cvt_pk_bf16_f32 v8, v9, v10
	v_cvt_pk_bf16_f32 v9, v11, v12
	global_load_dwordx4 v[10:13], v[20:21], off offset:3072 nt
	v_lshl_add_u32 v14, v25, 8, v23
	ds_read_b128 v[14:17], v14
	v_mad_i64_i32 v[18:19], s[0:1], v24, s48, v[2:3]
	v_add_u32_e32 v0, 20, v22
	global_store_dwordx4 v[18:19], v[6:9], off
	v_mad_i64_i32 v[20:21], s[0:1], v0, s51, v[4:5]
	s_waitcnt lgkmcnt(0)
	v_lshlrev_b32_e32 v6, 16, v14
	v_and_b32_e32 v7, 0xffff0000, v14
	v_lshlrev_b32_e32 v8, 16, v15
	v_and_b32_e32 v9, 0xffff0000, v15
	v_lshlrev_b32_e32 v14, 16, v16
	v_and_b32_e32 v15, 0xffff0000, v16
	v_lshlrev_b32_e32 v16, 16, v17
	v_and_b32_e32 v17, 0xffff0000, v17
	s_waitcnt vmcnt(1)
; __device__ __forceinline__ unsigned cvtpk(float lo, float hi) { unsigned r; asm volatile("v_cvt_pk_bf16_f32 %0, %1, %2" : "=v"(r) : "v"(lo), "v"(hi)); return r; }
; __device__ __forceinline__ float bflo(unsigned w) { return __uint_as_float(w << 16); }
; __device__ __forceinline__ float bfhi(unsigned w) { return __uint_as_float(w & 0xffff0000u); }
; __device__ __forceinline__ void attn_item(const bf16_t* __restrict__ Qb, const bf16_t* __restrict__ Kh, const bf16_t* __restrict__ Vh, const bf16_t* __restrict__ Zb, ...
;     ...
;   for (int i = 0; i < 8; ++i) { const int row = i * 4 + (lane_e >> 4), ch = lane_e & 15;
;     const u32x4 ov = *(const u32x4*)(stg + row * 128 + ch * 8); const u32x4 zv = *(const u32x4*)(Zw + (long)row * LDP + ch * 8);
;     u32x4 w; w.x = cvtpk(bflo(ov.x) * bflo(zv.x), bfhi(ov.x) * bfhi(zv.x)); w.y = cvtpk(bflo(ov.y) * bflo(zv.y), bfhi(ov.y) * bfhi(zv.y));
;     w.z = cvtpk(bflo(ov.z) * bflo(zv.z), bfhi(ov.z) * bfhi(zv.z)); w.w = cvtpk(bflo(ov.w) * bflo(zv.w), bfhi(ov.w) * bfhi(zv.w));
;     *(u32x4*)(Ow + (long)row * LDAF + ch * 8) = w; }
;   asm volatile("s_waitcnt lgkmcnt(0)" ::: "memory");
	v_lshlrev_b32_e32 v18, 16, v10
	v_and_b32_e32 v10, 0xffff0000, v10
	v_lshlrev_b32_e32 v19, 16, v11
	v_and_b32_e32 v11, 0xffff0000, v11
	v_lshlrev_b32_e32 v24, 16, v12
	v_and_b32_e32 v12, 0xffff0000, v12
	v_lshlrev_b32_e32 v26, 16, v13
	v_and_b32_e32 v13, 0xffff0000, v13
	v_mul_f32_e32 v6, v18, v6
	v_mul_f32_e32 v7, v10, v7
	v_mul_f32_e32 v8, v19, v8
	v_mul_f32_e32 v9, v11, v9
	v_mul_f32_e32 v10, v24, v14
	v_mul_f32_e32 v11, v12, v15
	v_mul_f32_e32 v12, v26, v16
	v_mul_f32_e32 v13, v13, v17
	v_cvt_pk_bf16_f32 v6, v6, v7
	v_cvt_pk_bf16_f32 v7, v8, v9
	v_cvt_pk_bf16_f32 v8, v10, v11
	v_cvt_pk_bf16_f32 v9, v12, v13
	global_load_dwordx4 v[10:13], v[20:21], off offset:3072 nt
	v_lshl_add_u32 v14, v0, 8, v23
	ds_read_b128 v[14:17], v14
	v_mad_i64_i32 v[18:19], s[0:1], v25, s48, v[2:3]
	v_add_u32_e32 v24, 24, v22
	global_store_dwordx4 v[18:19], v[6:9], off
	v_mad_i64_i32 v[20:21], s[0:1], v24, s51, v[4:5]
	s_waitcnt lgkmcnt(0)
	v_lshlrev_b32_e32 v6, 16, v14
	v_and_b32_e32 v7, 0xffff0000, v14
	v_lshlrev_b32_e32 v8, 16, v15
	v_and_b32_e32 v9, 0xffff0000, v15
	v_lshlrev_b32_e32 v14, 16, v16
	v_and_b32_e32 v15, 0xffff0000, v16
	v_lshlrev_b32_e32 v16, 16, v17
	v_and_b32_e32 v17, 0xffff0000, v17
	v_add_u32_e32 v22, 28, v22
	s_waitcnt vmcnt(1)
	v_lshlrev_b32_e32 v18, 16, v10
	v_and_b32_e32 v10, 0xffff0000, v10
	v_lshlrev_b32_e32 v19, 16, v11
	v_and_b32_e32 v11, 0xffff0000, v11
	v_lshlrev_b32_e32 v25, 16, v12
	v_and_b32_e32 v12, 0xffff0000, v12
	v_lshlrev_b32_e32 v26, 16, v13
	v_and_b32_e32 v13, 0xffff0000, v13
	v_mul_f32_e32 v6, v18, v6
	v_mul_f32_e32 v7, v10, v7
	v_mul_f32_e32 v8, v19, v8
	v_mul_f32_e32 v9, v11, v9
	v_mul_f32_e32 v10, v25, v14
	v_mul_f32_e32 v11, v12, v15
	v_mul_f32_e32 v12, v26, v16
	v_mul_f32_e32 v13, v13, v17
	v_cvt_pk_bf16_f32 v6, v6, v7
	v_cvt_pk_bf16_f32 v7, v8, v9
	v_cvt_pk_bf16_f32 v8, v10, v11
	v_cvt_pk_bf16_f32 v9, v12, v13
	global_load_dwordx4 v[10:13], v[20:21], off offset:3072 nt
	v_lshl_add_u32 v14, v24, 8, v23
	ds_read_b128 v[14:17], v14
	v_mad_i64_i32 v[18:19], s[0:1], v0, s48, v[2:3]
	v_mad_i64_i32 v[20:21], s[0:1], v22, s51, v[4:5]
	global_store_dwordx4 v[18:19], v[6:9], off
	s_waitcnt lgkmcnt(0)
	v_lshlrev_b32_e32 v0, 16, v14
	v_and_b32_e32 v4, 0xffff0000, v14
	v_lshlrev_b32_e32 v5, 16, v15
	v_and_b32_e32 v6, 0xffff0000, v15
	v_lshlrev_b32_e32 v7, 16, v16
	v_and_b32_e32 v8, 0xffff0000, v16
	v_lshlrev_b32_e32 v9, 16, v17
	v_and_b32_e32 v14, 0xffff0000, v17
	s_waitcnt vmcnt(1)
	v_lshlrev_b32_e32 v15, 16, v10
	v_and_b32_e32 v10, 0xffff0000, v10
	v_lshlrev_b32_e32 v16, 16, v11
	v_and_b32_e32 v11, 0xffff0000, v11
	v_lshlrev_b32_e32 v17, 16, v12
	v_and_b32_e32 v12, 0xffff0000, v12
	v_lshlrev_b32_e32 v18, 16, v13
	v_and_b32_e32 v13, 0xffff0000, v13
	v_mul_f32_e32 v4, v10, v4
	v_mul_f32_e32 v5, v16, v5
	v_mul_f32_e32 v6, v11, v6
	v_mul_f32_e32 v7, v17, v7
	v_mul_f32_e32 v8, v12, v8
	v_mul_f32_e32 v9, v18, v9
	v_mul_f32_e32 v10, v13, v14
	v_mul_f32_e32 v0, v15, v0
	v_cvt_pk_bf16_f32 v4, v0, v4
	v_cvt_pk_bf16_f32 v5, v5, v6
	v_cvt_pk_bf16_f32 v6, v7, v8
	v_cvt_pk_bf16_f32 v7, v9, v10
	global_load_dwordx4 v[8:11], v[20:21], off offset:3072 nt
	v_lshl_add_u32 v0, v22, 8, v23
	ds_read_b128 v[12:15], v0
	v_mad_i64_i32 v[16:17], s[0:1], v24, s48, v[2:3]
	v_mad_i64_i32 v[18:19], s[0:1], v22, s48, v[2:3]
	global_store_dwordx4 v[16:17], v[4:7], off
	s_waitcnt lgkmcnt(0)
	v_lshlrev_b32_e32 v0, 16, v12
	v_and_b32_e32 v2, 0xffff0000, v12
	v_lshlrev_b32_e32 v3, 16, v13
	v_and_b32_e32 v4, 0xffff0000, v13
	v_lshlrev_b32_e32 v5, 16, v14
	v_and_b32_e32 v6, 0xffff0000, v14
	v_lshlrev_b32_e32 v7, 16, v15
	v_and_b32_e32 v12, 0xffff0000, v15
	s_waitcnt vmcnt(1)
	v_lshlrev_b32_e32 v13, 16, v8
	v_and_b32_e32 v8, 0xffff0000, v8
	v_lshlrev_b32_e32 v14, 16, v9
	v_and_b32_e32 v9, 0xffff0000, v9
	v_lshlrev_b32_e32 v15, 16, v10
	v_and_b32_e32 v10, 0xffff0000, v10
	v_lshlrev_b32_e32 v16, 16, v11
	v_and_b32_e32 v11, 0xffff0000, v11
	v_mul_f32_e32 v2, v8, v2
	v_mul_f32_e32 v3, v14, v3
	v_mul_f32_e32 v4, v9, v4
	v_mul_f32_e32 v5, v15, v5
	v_mul_f32_e32 v0, v13, v0
	v_mul_f32_e32 v6, v10, v6
	v_mul_f32_e32 v7, v16, v7
	v_mul_f32_e32 v8, v11, v12
	v_cvt_pk_bf16_f32 v2, v0, v2
	v_cvt_pk_bf16_f32 v3, v3, v4
	v_cvt_pk_bf16_f32 v4, v5, v6
	v_cvt_pk_bf16_f32 v5, v7, v8
	global_store_dwordx4 v[18:19], v[2:5], off
	s_waitcnt lgkmcnt(0)
	s_barrier
	s_cbranch_scc1 .LBB0_479
; __device__ __forceinline__ void attn_item(const bf16_t* __restrict__ Qb, const bf16_t* __restrict__ Kh, const bf16_t* __restrict__ Vh, const bf16_t* __restrict__ Zb, ...
;   int tid_ = MYTID(wid_s); asm volatile("" : "+v"(tid_)); const int tid = tid_, wid = tid >> 6, lane = tid & 63, r32 = lane & 31, hi = lane >> 5;
;   constexpr int SLOT = 32768, KOFF = 16384, WSOFF = 3 * SLOT;
;   float* ws = (float*)(lds + WSOFF) + wid * 64; float* al_l = ws + 32;
;   float m_reg = 0.f, l_reg = 0; f32x16 o[4] = {}; bf16x8 qr[8]; f32x16 negm = f32x16{}; asm volatile("" : "+v"(negm));
;   const bf16_t* Qw = Qb + (long)(wid * QBLK + r32) * LDQ + hi * 8;
;   float qn2 = 0.f;
;   {
;     u32x4 qw[8];
; #pragma unroll
;     for (int d0 = 0; d0 < 8; ++d0) qw[d0] = *reinterpret_cast<const u32x4*>(Qw + d0 * 16);
;     float ss = 0.f;
; #pragma unroll
;     for (int d0 = 0; d0 < 8; ++d0) { const float a0 = bflo(qw[d0].x), a1 = bfhi(qw[d0].x), a2 = bflo(qw[d0].y), a3 = bfhi(qw[d0].y), a4 = bflo(qw[d0].z), a5 = bfhi(qw[d0].z), a6 = bflo(qw[d0].w), a7 = bfhi(qw[d0].w);
;       ss += (a0 * a0 + a1 * a1) + (a2 * a2 + a3 * a3) + (a4 * a4 + a5 * a5) + (a6 * a6 + a7 * a7); }
;     { auto rr = __builtin_amdgcn_permlane32_swap(__float_as_uint(ss), __float_as_uint(ss), false, false); ss = __uint_as_float(rr[0]) + __uint_as_float(rr[1]); }
;     const float rstd = __builtin_amdgcn_rsqf(ss * (1.0f / 128.0f) + NORM_EPS) * (SCALE * 1.4426950408889634f);
;     const int hq = lane_id_asm() >> 5;
;     const int spos = qpos0 + wid * QBLK + r32; const float prow = (float)(spos >> 6), pcol = (float)(spos & 63);
; #pragma unroll
;     for (int bb = 0; bb < 4; ++bb) { const int d1 = (bb & 1) + 4 * (bb >> 1), d2 = d1 + 2;
;       const float pos = (bb < 2) ? prow : pcol; const float* g1p = qg + d1 * 16 + hq * 8; const float* g2p = qg + d2 * 16 + hq * 8;
; __global__ void __launch_bounds__(512, 2) fwd_megakernel(Args a) {
;     ...
;     const int xx = it & 7, rest = it >> 3, bk = xx >> 1, qb = (xx & 1) * 32 + (rest & 31), hq = rest >> 5, kvh = bk & 1, h = kvh * 4 + hq, b = bk >> 1;
;     const long row0 = (long)b * SEQ + qb * 256;
;     att::attn_item(P1 + row0 * LDP + C_Q + h * 128, P1 + (long)b * SEQ * LDP + C_K + kvh * 128, P1 + (long)b * SEQ * LDP + C_V + kvh * 128,
;                    P1 + row0 * LDP + C_ZA + h * 128, AF + row0 * LDAF + h * 128, SEQ, (char*)lds, wid_s, a.in[3], qb * 256, kmaxg);
.LBB0_452:
	s_lshl_b32 s0, s70, 5
	s_and_b32 s0, s0, 32
	s_bfe_u32 s7, s70, 0x50003
	s_or_b32 s7, s0, s7
	s_lshl_b32 s0, s70, 12
	s_and_b32 s0, s0, 0x4000
	s_lshl_b32 s7, s7, 8
	s_bfe_u32 s1, s70, 0x10001
	s_or_b32 s71, s7, s0
	s_bfe_u32 s6, s54, 0x1000e
	s_lshl_b32 s8, s1, 8
	s_mul_i32 s9, s71, 0x2080
	s_add_u32 s9, s42, s9
	s_addc_u32 s36, s43, 0
	s_ashr_i32 s24, s70, 1
	s_lshl_b32 s1, s1, 9
	s_and_b32 s24, s24, 0xffffff80
	s_add_i32 s24, s1, s24
	s_ashr_i32 s25, s24, 31
	s_lshl_b64 s[26:27], s[24:25], 1
	s_add_u32 s24, s9, s26
	v_mbcnt_lo_u32_b32 v0, -1, 0
	v_mbcnt_hi_u32_b32 v0, -1, v0
	s_addc_u32 s25, s36, s27
	v_add_u32_e32 v186, s33, v0
	v_mov_b64_e32 v[2:3], s[24:25]
	v_ashrrev_i32_e32 v0, 1, v186
	v_and_b32_e32 v4, 0xffffffe0, v0
	v_bfi_b32 v0, s57, v0, v186
	v_lshrrev_b32_e32 v188, 1, v186
	v_mad_i64_i32 v[2:3], s[36:37], v0, s51, v[2:3]
	v_and_b32_e32 v212, 16, v188
	v_mov_b32_e32 v213, v1
	v_mov_b32_e32 v16, v1
	v_mov_b32_e32 v17, v1
	v_mov_b32_e32 v18, v1
	v_mov_b32_e32 v19, v1
	v_mov_b32_e32 v20, v1
	v_mov_b32_e32 v21, v1
	v_mov_b32_e32 v22, v1
	v_mov_b32_e32 v23, v1
	v_mov_b32_e32 v24, v1
	v_mov_b32_e32 v25, v1
	v_mov_b32_e32 v26, v1
	v_mov_b32_e32 v27, v1
	v_mov_b32_e32 v28, v1
	v_mov_b32_e32 v29, v1
	v_mov_b32_e32 v30, v1
	v_mov_b32_e32 v31, v1
	v_lshl_add_u64 v[2:3], v[2:3], 0, v[212:213]
	global_load_dwordx4 v[36:39], v[2:3], off nt
	global_load_dwordx4 v[44:47], v[2:3], off offset:32 nt
	global_load_dwordx4 v[40:43], v[2:3], off offset:64 nt
	global_load_dwordx4 v[48:51], v[2:3], off offset:96 nt
	global_load_dwordx4 v[52:55], v[2:3], off offset:128 nt
	global_load_dwordx4 v[60:63], v[2:3], off offset:160 nt
	global_load_dwordx4 v[56:59], v[2:3], off offset:192 nt
	global_load_dwordx4 v[64:67], v[2:3], off offset:224 nt
	v_mbcnt_lo_u32_b32 v0, -1, 0
	v_mbcnt_hi_u32_b32 v0, -1, v0
	v_and_b32_e32 v187, 31, v186
	v_ashrrev_i32_e32 v0, 2, v0
	v_and_b32_e32 v78, -8, v0
	v_or_b32_e32 v69, 1, v78
	v_cvt_f32_i32_e32 v69, v69
	v_cvt_f32_i32_e32 v6, v78
	v_or_b32_e32 v2, s7, v187
	s_waitcnt vmcnt(22)
	v_add_u32_e32 v136, v2, v4
	v_mul_f32_e32 v69, 0xbed49a78, v69
	v_exp_f32_e32 v69, v69
	v_mul_f32_e32 v6, 0xbed49a78, v6
	v_ashrrev_i32_e32 v2, 6, v136
	v_exp_f32_e32 v68, v6
	v_mul_f32_e32 v138, 0.15915494, v69
	v_or_b32_e32 v69, 2, v78
	s_waitcnt vmcnt(20)
	v_cvt_f32_i32_e32 v145, v2
	v_cvt_f32_i32_e32 v69, v69
	v_ashrrev_i32_e32 v79, 31, v78
	v_lshl_add_u64 v[14:15], v[78:79], 2, s[18:19]
	global_load_dwordx4 v[10:13], v[14:15], off
	global_load_dwordx4 v[2:5], v[14:15], off offset:16
	global_load_dwordx4 v[32:35], v[14:15], off offset:128
	global_load_dwordx4 v[6:9], v[14:15], off offset:144
	v_mul_f32_e32 v137, 0.15915494, v68
	v_mul_f32_e32 v68, v137, v145
	v_mul_f32_e32 v69, 0xbed49a78, v69
	v_floor_f32_e32 v68, v68
	v_exp_f32_e32 v69, v69
	v_fma_f32 v68, v137, v145, -v68
	v_sin_f32_e32 v104, v68
	v_cos_f32_e32 v105, v68
	v_mul_f32_e32 v68, v138, v145
	v_floor_f32_e32 v68, v68
	v_fma_f32 v68, v138, v145, -v68
	v_mul_f32_e32 v139, 0.15915494, v69
	v_sin_f32_e32 v83, v68
	v_cos_f32_e32 v82, v68
	v_or_b32_e32 v68, 3, v78
	v_mul_f32_e32 v69, v139, v145
	v_cvt_f32_i32_e32 v68, v68
	v_floor_f32_e32 v69, v69
	v_fma_f32 v69, v139, v145, -v69
	v_sin_f32_e32 v106, v69
	v_cos_f32_e32 v107, v69
	v_or_b32_e32 v69, 4, v78
	v_cvt_f32_i32_e32 v69, v69
	v_mul_f32_e32 v68, 0xbed49a78, v68
	v_exp_f32_e32 v68, v68
	v_or_b32_e32 v0, 7, v0
	v_mul_f32_e32 v69, 0xbed49a78, v69
	v_exp_f32_e32 v69, v69
	v_mul_f32_e32 v140, 0.15915494, v68
	v_mul_f32_e32 v68, v140, v145
	v_floor_f32_e32 v68, v68
	v_fma_f32 v68, v140, v145, -v68
	v_mul_f32_e32 v141, 0.15915494, v69
	v_sin_f32_e32 v97, v68
	v_cos_f32_e32 v96, v68
	v_or_b32_e32 v68, 5, v78
	v_mul_f32_e32 v69, v141, v145
	v_cvt_f32_i32_e32 v68, v68
	v_floor_f32_e32 v69, v69
	v_fma_f32 v69, v141, v145, -v69
	v_sin_f32_e32 v108, v69
	v_cos_f32_e32 v109, v69
	v_or_b32_e32 v69, 6, v78
	v_cvt_f32_i32_e32 v69, v69
	v_mul_f32_e32 v68, 0xbed49a78, v68
	v_exp_f32_e32 v68, v68
	v_cvt_f32_i32_e32 v0, v0
	v_mul_f32_e32 v69, 0xbed49a78, v69
	v_exp_f32_e32 v69, v69
	v_mul_f32_e32 v142, 0.15915494, v68
	v_mul_f32_e32 v68, v142, v145
	v_floor_f32_e32 v68, v68
	v_fma_f32 v68, v142, v145, -v68
	v_mul_f32_e32 v143, 0.15915494, v69
	v_mul_f32_e32 v0, 0xbed49a78, v0
	v_sin_f32_e32 v101, v68
	v_cos_f32_e32 v100, v68
	v_mul_f32_e32 v68, v143, v145
	v_exp_f32_e32 v0, v0
	v_floor_f32_e32 v68, v68
	v_fma_f32 v68, v143, v145, -v68
	v_sin_f32_e32 v110, v68
	v_cos_f32_e32 v111, v68
	v_add_u32_e32 v68, 16, v78
	v_mul_f32_e32 v144, 0.15915494, v0
	v_cvt_f32_i32_e32 v68, v68
	v_mul_f32_e32 v0, v144, v145
	v_floor_f32_e32 v0, v0
	v_fma_f32 v0, v144, v145, -v0
	v_sin_f32_e32 v99, v0
	v_cos_f32_e32 v98, v0
	v_mul_f32_e32 v0, 0xbed49a78, v68
	s_waitcnt vmcnt(5)
; __device__ __forceinline__ float bflo(unsigned w) { return __uint_as_float(w << 16); }
; __device__ __forceinline__ float bfhi(unsigned w) { return __uint_as_float(w & 0xffff0000u); }
; __device__ __forceinline__ void attn_item(const bf16_t* __restrict__ Qb, const bf16_t* __restrict__ Kh, const bf16_t* __restrict__ Vh, const bf16_t* __restrict__ Zb, ...
;     ...
;     float ss = 0.f;
; #pragma unroll
;     for (int d0 = 0; d0 < 8; ++d0) { const float a0 = bflo(qw[d0].x), a1 = bfhi(qw[d0].x), a2 = bflo(qw[d0].y), a3 = bfhi(qw[d0].y), a4 = bflo(qw[d0].z), a5 = bfhi(qw[d0].z), a6 = bflo(qw[d0].w), a7 = bfhi(qw[d0].w);
;       ss += (a0 * a0 + a1 * a1) + (a2 * a2 + a3 * a3) + (a4 * a4 + a5 * a5) + (a6 * a6 + a7 * a7); }
	v_lshlrev_b32_e32 v93, 16, v57
	v_and_b32_e32 v91, 0xffff0000, v57
	v_and_b32_e32 v155, 0xffff0000, v43
	v_and_b32_e32 v157, 0xffff0000, v42
	v_exp_f32_e32 v79, v0
	v_mov_b32_e32 v94, v93
	v_mov_b32_e32 v95, v91
	v_mul_f32_e32 v0, v91, v91
	v_lshlrev_b32_e32 v113, 16, v49
	v_and_b32_e32 v123, 0xffff0000, v49
	v_lshlrev_b32_e32 v57, 16, v43
	v_lshlrev_b32_e32 v49, 16, v42
	v_mov_b32_e32 v42, v155
	v_mov_b32_e32 v43, v157
	v_pk_fma_f32 v[150:151], v[94:95], v[94:95], v[0:1] op_sel_hi:[1,1,0]
	v_lshlrev_b32_e32 v103, 16, v56
	v_and_b32_e32 v95, 0xffff0000, v56
	v_lshlrev_b32_e32 v125, 16, v48
	v_and_b32_e32 v117, 0xffff0000, v48
	v_lshlrev_b32_e32 v56, 16, v39
	v_and_b32_e32 v154, 0xffff0000, v39
	v_lshlrev_b32_e32 v48, 16, v38
	v_and_b32_e32 v156, 0xffff0000, v38
	v_mov_b32_e32 v38, v57
	v_mov_b32_e32 v39, v49
	v_pk_mul_f32 v[42:43], v[42:43], v[42:43]
	v_and_b32_e32 v159, 0xffff0000, v41
	v_pk_fma_f32 v[38:39], v[38:39], v[38:39], v[42:43]
	v_lshlrev_b32_e32 v43, 16, v41
	v_and_b32_e32 v41, 0xffff0000, v40
	v_and_b32_e32 v118, 0xffff0000, v47
	v_lshlrev_b32_e32 v161, 16, v40
	v_mov_b32_e32 v162, v41
	v_mov_b32_e32 v163, v159
	v_and_b32_e32 v70, 0xffff0000, v63
	v_lshlrev_b32_e32 v72, 16, v62
	v_and_b32_e32 v62, 0xffff0000, v62
	v_lshlrev_b32_e32 v114, 16, v47
	v_and_b32_e32 v120, 0xffff0000, v46
	v_lshlrev_b32_e32 v42, 16, v37
	v_and_b32_e32 v158, 0xffff0000, v37
	v_lshlrev_b32_e32 v160, 16, v36
	v_and_b32_e32 v40, 0xffff0000, v36
	v_mov_b32_e32 v36, v161
	v_mov_b32_e32 v37, v43
	v_pk_mul_f32 v[162:163], v[162:163], v[162:163]
	v_mov_b32_e32 v164, v154
	v_mov_b32_e32 v165, v118
	v_lshlrev_b32_e32 v68, 16, v63
	v_mov_b32_e32 v74, v70
	v_mov_b32_e32 v75, v62
	v_lshlrev_b32_e32 v126, 16, v46
	v_and_b32_e32 v122, 0xffff0000, v45
	v_pk_fma_f32 v[36:37], v[36:37], v[36:37], v[162:163]
	v_mov_b32_e32 v162, v56
	v_mov_b32_e32 v163, v114
	v_pk_mul_f32 v[164:165], v[164:165], v[164:165]
	v_mov_b32_e32 v166, v156
	v_mov_b32_e32 v167, v120
	s_waitcnt vmcnt(4)
	v_lshlrev_b32_e32 v69, 16, v67
	v_and_b32_e32 v71, 0xffff0000, v67
	v_lshlrev_b32_e32 v73, 16, v66
	v_and_b32_e32 v63, 0xffff0000, v66
	v_mov_b32_e32 v66, v68
	v_mov_b32_e32 v67, v72
	v_pk_mul_f32 v[74:75], v[74:75], v[74:75]
	v_lshlrev_b32_e32 v112, 16, v45
	v_and_b32_e32 v116, 0xffff0000, v44
	v_pk_fma_f32 v[162:163], v[162:163], v[162:163], v[164:165]
	v_mov_b32_e32 v164, v48
	v_mov_b32_e32 v165, v126
	v_pk_mul_f32 v[166:167], v[166:167], v[166:167]
	v_mov_b32_e32 v168, v158
	v_mov_b32_e32 v169, v122
	v_pk_fma_f32 v[80:81], v[66:67], v[66:67], v[74:75]
	v_and_b32_e32 v66, 0xffff0000, v61
	v_lshlrev_b32_e32 v76, 16, v60
	v_and_b32_e32 v60, 0xffff0000, v60
	v_lshlrev_b32_e32 v124, 16, v44
	v_pk_fma_f32 v[164:165], v[164:165], v[164:165], v[166:167]
	v_mov_b32_e32 v166, v42
	v_mov_b32_e32 v167, v112
	v_pk_mul_f32 v[168:169], v[168:169], v[168:169]
	v_mov_b32_e32 v170, v40
	v_mov_b32_e32 v171, v116
	v_lshlrev_b32_e32 v74, 16, v61
	v_mov_b32_e32 v84, v60
	v_mov_b32_e32 v85, v66
	v_pk_fma_f32 v[166:167], v[166:167], v[166:167], v[168:169]
	v_mov_b32_e32 v168, v160
	v_mov_b32_e32 v169, v124
	v_pk_mul_f32 v[170:171], v[170:171], v[170:171]
	v_lshlrev_b32_e32 v75, 16, v65
	v_and_b32_e32 v67, 0xffff0000, v65
	v_lshlrev_b32_e32 v77, 16, v64
	v_and_b32_e32 v61, 0xffff0000, v64
	v_mov_b32_e32 v64, v76
	v_mov_b32_e32 v65, v74
	v_pk_mul_f32 v[84:85], v[84:85], v[84:85]
	v_pk_fma_f32 v[168:169], v[168:169], v[168:169], v[170:171]
	v_pk_fma_f32 v[64:65], v[64:65], v[64:65], v[84:85]
	v_lshlrev_b32_e32 v92, 16, v53
	v_and_b32_e32 v90, 0xffff0000, v53
	v_lshlrev_b32_e32 v102, 16, v52
	v_and_b32_e32 v94, 0xffff0000, v52
	v_mov_b32_e32 v52, v103
	v_mov_b32_e32 v53, v95
	v_mul_f32_e32 v0, v95, v95
	v_pk_add_f32 v[166:167], v[168:169], v[166:167]
	v_pk_add_f32 v[64:65], v[64:65], v[64:65] op_sel:[0,1] op_sel_hi:[1,0]
	v_and_b32_e32 v87, 0xffff0000, v58
	v_and_b32_e32 v86, 0xffff0000, v54
	v_pk_fma_f32 v[52:53], v[52:53], v[52:53], v[0:1] op_sel_hi:[1,1,0]
	v_and_b32_e32 v119, 0xffff0000, v51
	v_mov_b32_e32 v46, v113
	v_mov_b32_e32 v47, v123
	v_mul_f32_e32 v0, v123, v123
	v_pk_add_f32 v[36:37], v[36:37], v[36:37] op_sel:[0,1] op_sel_hi:[1,0]
	v_pk_add_f32 v[164:165], v[164:165], v[166:167]
	v_pk_add_f32 v[64:65], v[80:81], v[64:65] op_sel:[1,0] op_sel_hi:[0,1]
	v_lshlrev_b32_e32 v89, 16, v58
	v_lshlrev_b32_e32 v88, 16, v54
	v_lshlrev_b32_e32 v115, 16, v51
	v_and_b32_e32 v121, 0xffff0000, v50
	v_pk_fma_f32 v[46:47], v[46:47], v[46:47], v[0:1] op_sel_hi:[1,1,0]
	v_mov_b32_e32 v44, v125
	v_mov_b32_e32 v45, v117
	v_mul_f32_e32 v0, v117, v117
	v_pk_add_f32 v[36:37], v[38:39], v[36:37] op_sel:[1,0] op_sel_hi:[0,1]
	v_pk_add_f32 v[162:163], v[162:163], v[164:165]
	v_pk_mov_b32 v[164:165], v[118:119], v[86:87] op_sel:[1,0]
	v_pk_add_f32 v[64:65], v[80:81], v[64:65]
	v_lshlrev_b32_e32 v85, 16, v59
	v_lshlrev_b32_e32 v84, 16, v55
	v_and_b32_e32 v81, 0xffff0000, v59
	v_and_b32_e32 v80, 0xffff0000, v55
	v_pk_mul_f32 v[54:55], v[92:93], v[92:93]
	v_pk_mul_f32 v[58:59], v[90:91], v[90:91]
	v_lshlrev_b32_e32 v127, 16, v50
	v_pk_fma_f32 v[44:45], v[44:45], v[44:45], v[0:1] op_sel_hi:[1,1,0]
	v_pk_add_f32 v[36:37], v[38:39], v[36:37]
	v_pk_add_f32 v[38:39], v[162:163], v[162:163] op_sel:[0,1] op_sel_hi:[1,0]
	v_pk_mov_b32 v[162:163], v[114:115], v[88:89] op_sel:[1,0]
	v_pk_mul_f32 v[164:165], v[164:165], v[164:165]
	v_pk_mov_b32 v[166:167], v[120:121], v[94:95] op_sel:[1,0]
	v_pk_fma_f32 v[162:163], v[162:163], v[162:163], v[164:165]
	v_pk_mov_b32 v[164:165], v[126:127], v[102:103] op_sel:[1,0]
	v_pk_mul_f32 v[166:167], v[166:167], v[166:167]
	v_mov_b32_e32 v45, v54
	v_mov_b32_e32 v47, v58
	v_pk_mul_f32 v[146:147], v[84:85], v[84:85]
	v_pk_mul_f32 v[148:149], v[80:81], v[80:81]
	v_pk_fma_f32 v[164:165], v[164:165], v[164:165], v[166:167]
	v_pk_add_f32 v[44:45], v[44:45], v[46:47]
	v_mov_b32_e32 v39, v146
	v_pk_add_f32 v[44:45], v[164:165], v[44:45]
	v_mov_b32_e32 v37, v148
	v_pk_add_f32 v[44:45], v[162:163], v[44:45]
	v_pk_add_f32 v[36:37], v[38:39], v[36:37]
	v_pk_mul_f32 v[132:133], v[74:75], v[74:75]
	v_pk_add_f32 v[36:37], v[36:37], v[44:45]
	v_mov_b32_e32 v44, v81
	v_mov_b32_e32 v45, v63
	v_pk_mul_f32 v[134:135], v[66:67], v[66:67]
	v_mov_b32_e32 v38, v85
	v_mov_b32_e32 v39, v73
	v_pk_mul_f32 v[44:45], v[44:45], v[44:45]
	v_mov_b32_e32 v46, v87
	v_mov_b32_e32 v47, v61
	v_pk_fma_f32 v[38:39], v[38:39], v[38:39], v[44:45]
	v_mov_b32_e32 v44, v89
	v_mov_b32_e32 v45, v77
	v_pk_mul_f32 v[46:47], v[46:47], v[46:47]
	v_mov_b32_e32 v53, v133
	v_mov_b32_e32 v151, v135
	v_pk_mul_f32 v[128:129], v[68:69], v[68:69]
	v_pk_mul_f32 v[130:131], v[70:71], v[70:71]
	v_pk_add_f32 v[36:37], v[36:37], v[36:37] op_sel:[0,1] op_sel_hi:[1,0]
	v_pk_fma_f32 v[44:45], v[44:45], v[44:45], v[46:47]
	v_pk_add_f32 v[46:47], v[52:53], v[150:151]
	v_mov_b32_e32 v37, v129
	v_pk_add_f32 v[44:45], v[44:45], v[46:47]
	v_mov_b32_e32 v65, v131
	v_pk_add_f32 v[38:39], v[38:39], v[44:45]
	v_pk_add_f32 v[36:37], v[36:37], v[64:65]
	s_waitcnt vmcnt(2)
; __device__ __forceinline__ int lane_id_asm() { int r; asm volatile("v_mbcnt_lo_u32_b32 %0, -1, 0\n\tv_mbcnt_hi_u32_b32 %0, -1, %0" : "=v"(r)); return r; }
; __device__ __forceinline__ float bflo(unsigned w) { return __uint_as_float(w << 16); }
; __device__ __forceinline__ void attn_item(const bf16_t* __restrict__ Qb, const bf16_t* __restrict__ Kh, const bf16_t* __restrict__ Vh, const bf16_t* __restrict__ Zb, ...
;     ...
;     { auto rr = __builtin_amdgcn_permlane32_swap(__float_as_uint(ss), __float_as_uint(ss), false, false); ss = __uint_as_float(rr[0]) + __uint_as_float(rr[1]); }
;     const float rstd = __builtin_amdgcn_rsqf(ss * (1.0f / 128.0f) + NORM_EPS) * (SCALE * 1.4426950408889634f);
;     const int hq = lane_id_asm() >> 5;
;     const int spos = qpos0 + wid * QBLK + r32; const float prow = (float)(spos >> 6), pcol = (float)(spos & 63);
; #pragma unroll
;     for (int bb = 0; bb < 4; ++bb) { const int d1 = (bb & 1) + 4 * (bb >> 1), d2 = d1 + 2;
;       const float pos = (bb < 2) ? prow : pcol; const float* g1p = qg + d1 * 16 + hq * 8; const float* g2p = qg + d2 * 16 + hq * 8;
;       const f32x4 g1a = *(const f32x4*)g1p, g1b = *(const f32x4*)(g1p + 4), g2a = *(const f32x4*)g2p, g2b = *(const f32x4*)(g2p + 4);
;       float o1[8], o2[8];
; #pragma unroll
;       for (int e = 0; e < 8; ++e) { const unsigned w1 = (e < 2) ? qw[d1].x : (e < 4) ? qw[d1].y : (e < 6) ? qw[d1].z : qw[d1].w, w2 = (e < 2) ? qw[d2].x : (e < 4) ? qw[d2].y : (e < 6) ? qw[d2].z : qw[d2].w;
;         const float x1 = (e & 1) ? bfhi(w1) : bflo(w1), x2 = (e & 1) ? bfhi(w2) : bflo(w2); const float ga = (e < 4) ? g1a[e & 3] : g1b[e & 3], gb = (e < 4) ? g2a[e & 3] : g2b[e & 3];
;         const int fi = (d1 & 1) * 16 + hq * 8 + e; float rev = pos * (__builtin_amdgcn_exp2f(-(float)fi * (13.287712379549449f / 32.0f)) * 0.15915494309189535f); rev -= floorf(rev);
;         const float sn = sin_rev(rev), cs = cos_rev(rev), y1 = x1 * rstd * ga, y2 = x2 * rstd * gb; o1[e] = y1 * cs - y2 * sn; o2[e] = y2 * cs + y1 * sn; }
; #pragma unroll
;       for (int e = 0; e < 8; ++e) qn2 += o1[e] * o1[e] + o2[e] * o2[e];
;       u32x4 p1 = {cvtpk(o1[0], o1[1]), cvtpk(o1[2], o1[3]), cvtpk(o1[4], o1[5]), cvtpk(o1[6], o1[7])}, p2 = {cvtpk(o2[0], o2[1]), cvtpk(o2[2], o2[3]), cvtpk(o2[4], o2[5]), cvtpk(o2[6], o2[7])};
;       qr[d1] = *reinterpret_cast<bf16x8*>(&p1); qr[d2] = *reinterpret_cast<bf16x8*>(&p2); }
	v_mov_b32_e32 v50, v2
	v_pk_add_f32 v[36:37], v[36:37], v[38:39]
	v_mov_b32_e32 v128, v12
	v_pk_add_f32 v[36:37], v[36:37], v[36:37] op_sel:[0,1] op_sel_hi:[1,0]
	s_waitcnt vmcnt(1)
	v_mov_b32_e32 v129, v34
	v_mov_b32_e32 v0, v36
	s_nop 1
	v_permlane32_swap_b32_e32 v36, v0
	v_add_f32_e32 v0, v36, v0
	v_fmamk_f32 v0, v0, 0x3c000000, v217
	v_rsq_f32_e32 v0, v0
	v_mov_b32_e32 v36, v10
	v_mov_b32_e32 v37, v32
	v_mov_b32_e32 v32, v11
	v_mul_f32_e32 v0, 0x3e0293ee, v0
	v_pk_mul_f32 v[38:39], v[0:1], v[160:161] op_sel_hi:[0,1]
	v_pk_mul_f32 v[38:39], v[36:37], v[38:39]
	v_mov_b32_e32 v36, v105
	v_mov_b32_e32 v37, v104
	v_mul_f32_e32 v2, v39, v104
	v_pk_mul_f32 v[40:41], v[0:1], v[40:41] op_sel_hi:[0,1]
	v_pk_fma_f32 v[36:37], v[38:39], v[36:37], v[2:3] op_sel_hi:[1,1,0] neg_lo:[0,0,1] neg_hi:[0,0,1]
	v_mul_f32_e32 v2, v39, v105
	v_pk_mul_f32 v[10:11], v[32:33], v[40:41]
	v_pk_fma_f32 v[38:39], v[38:39], v[104:105], v[2:3] op_sel_hi:[1,1,0]
	v_mul_f32_e32 v2, v11, v83
	v_pk_fma_f32 v[32:33], v[10:11], v[82:83], v[2:3] op_sel_hi:[1,1,0] neg_lo:[0,0,1] neg_hi:[0,0,1]
	v_mov_b32_e32 v40, v83
	v_mov_b32_e32 v41, v82
	v_mul_f32_e32 v2, v11, v82
	v_pk_fma_f32 v[40:41], v[10:11], v[40:41], v[2:3] op_sel_hi:[1,1,0]
	v_pk_mul_f32 v[10:11], v[0:1], v[42:43] op_sel_hi:[0,1]
	v_pk_mul_f32 v[10:11], v[128:129], v[10:11]
	v_mov_b32_e32 v42, v107
	v_mov_b32_e32 v43, v106
	v_mul_f32_e32 v2, v11, v106
	v_pk_fma_f32 v[42:43], v[10:11], v[42:43], v[2:3] op_sel_hi:[1,1,0] neg_lo:[0,0,1] neg_hi:[0,0,1]
	v_mul_f32_e32 v2, v11, v107
	v_pk_fma_f32 v[44:45], v[10:11], v[106:107], v[2:3] op_sel_hi:[1,1,0]
	v_pk_mul_f32 v[10:11], v[0:1], v[158:159] op_sel_hi:[0,1]
	v_mov_b32_e32 v34, v13
	v_pk_mul_f32 v[10:11], v[34:35], v[10:11]
	v_mov_b32_e32 v12, v97
	v_mul_f32_e32 v2, v11, v97
	v_pk_fma_f32 v[34:35], v[10:11], v[96:97], v[2:3] op_sel_hi:[1,1,0] neg_lo:[0,0,1] neg_hi:[0,0,1]
	v_mov_b32_e32 v13, v96
	v_mul_f32_e32 v2, v11, v96
	s_waitcnt vmcnt(0)
	v_mov_b32_e32 v51, v6
	v_pk_fma_f32 v[46:47], v[10:11], v[12:13], v[2:3] op_sel_hi:[1,1,0]
	v_pk_mul_f32 v[10:11], v[0:1], v[48:49] op_sel_hi:[0,1]
	v_pk_mul_f32 v[10:11], v[50:51], v[10:11]
	v_mov_b32_e32 v12, v109
	v_mov_b32_e32 v13, v108
	v_mul_f32_e32 v2, v11, v108
	v_pk_fma_f32 v[48:49], v[10:11], v[12:13], v[2:3] op_sel_hi:[1,1,0] neg_lo:[0,0,1] neg_hi:[0,0,1]
	v_mul_f32_e32 v2, v11, v109
	v_pk_fma_f32 v[50:51], v[10:11], v[108:109], v[2:3] op_sel_hi:[1,1,0]
	v_pk_mul_f32 v[10:11], v[0:1], v[156:157] op_sel_hi:[0,1]
	v_mov_b32_e32 v6, v3
	v_pk_mul_f32 v[2:3], v[6:7], v[10:11]
	v_mov_b32_e32 v152, v4
	v_mul_f32_e32 v4, v3, v101
	v_pk_fma_f32 v[52:53], v[2:3], v[100:101], v[4:5] op_sel_hi:[1,1,0] neg_lo:[0,0,1] neg_hi:[0,0,1]
	v_mov_b32_e32 v6, v101
	v_mov_b32_e32 v7, v100
	v_mul_f32_e32 v4, v3, v100
	v_mov_b32_e32 v153, v8
	v_pk_fma_f32 v[54:55], v[2:3], v[6:7], v[4:5] op_sel_hi:[1,1,0]
	v_pk_mul_f32 v[2:3], v[0:1], v[56:57] op_sel_hi:[0,1]
	v_pk_mul_f32 v[2:3], v[152:153], v[2:3]
	v_mov_b32_e32 v6, v111
	v_mov_b32_e32 v7, v110
	v_mul_f32_e32 v4, v3, v110
	v_pk_fma_f32 v[56:57], v[2:3], v[6:7], v[4:5] op_sel_hi:[1,1,0] neg_lo:[0,0,1] neg_hi:[0,0,1]
	v_mul_f32_e32 v4, v3, v111
	v_pk_fma_f32 v[58:59], v[2:3], v[110:111], v[4:5] op_sel_hi:[1,1,0]
	v_pk_mul_f32 v[2:3], v[0:1], v[154:155] op_sel_hi:[0,1]
	v_mov_b32_e32 v8, v5
	v_pk_mul_f32 v[2:3], v[8:9], v[2:3]
	v_cvt_pk_bf16_f32 v152, v36, v32
	v_cvt_pk_bf16_f32 v153, v42, v34
	v_cvt_pk_bf16_f32 v154, v48, v52
	v_add_u32_e32 v96, 17, v78
	v_mul_f32_e32 v4, v3, v99
	v_pk_fma_f32 v[64:65], v[2:3], v[98:99], v[4:5] op_sel_hi:[1,1,0] neg_lo:[0,0,1] neg_hi:[0,0,1]
	v_mov_b32_e32 v4, v99
	v_mov_b32_e32 v5, v98
	v_mul_f32_e32 v6, v3, v98
	v_pk_fma_f32 v[82:83], v[2:3], v[4:5], v[6:7] op_sel_hi:[1,1,0]
	v_cvt_pk_bf16_f32 v155, v56, v64
	v_cvt_pk_bf16_f32 v148, v38, v40
	v_cvt_pk_bf16_f32 v149, v44, v46
	v_cvt_pk_bf16_f32 v150, v50, v54
	v_cvt_f32_i32_e32 v96, v96
	v_cvt_pk_bf16_f32 v151, v58, v82
	global_load_dwordx4 v[2:5], v[14:15], off offset:80
	global_load_dwordx4 v[6:9], v[14:15], off offset:64
	global_load_dwordx4 v[10:13], v[14:15], off offset:192
	global_load_dwordx4 v[128:131], v[14:15], off offset:208
	v_mul_f32_e32 v176, 0.15915494, v79
	v_mul_f32_e32 v96, 0xbed49a78, v96
	v_exp_f32_e32 v98, v96
	v_mul_f32_e32 v79, v176, v145
	v_floor_f32_e32 v79, v79
	v_fma_f32 v79, v176, v145, -v79
	v_mul_f32_e32 v177, 0.15915494, v98
	v_add_u32_e32 v98, 18, v78
	v_cvt_f32_i32_e32 v98, v98
	v_sin_f32_e32 v96, v79
	v_cos_f32_e32 v97, v79
	v_mul_f32_e32 v79, v177, v145
	v_floor_f32_e32 v79, v79
	v_fma_f32 v79, v177, v145, -v79
	v_mul_f32_e32 v98, 0xbed49a78, v98
	v_sin_f32_e32 v99, v79
	v_exp_f32_e32 v100, v98
	v_cos_f32_e32 v98, v79
	v_add_u32_e32 v79, 19, v78
	v_cvt_f32_i32_e32 v79, v79
	v_add_u32_e32 v104, 20, v78
	v_cvt_f32_i32_e32 v104, v104
	v_mul_f32_e32 v178, 0.15915494, v100
	v_mul_f32_e32 v79, 0xbed49a78, v79
	v_exp_f32_e32 v79, v79
	v_mul_f32_e32 v104, 0xbed49a78, v104
	v_exp_f32_e32 v104, v104
	v_mul_f32_e32 v100, v178, v145
	v_mul_f32_e32 v179, 0.15915494, v79
	v_mul_f32_e32 v79, v179, v145
	v_floor_f32_e32 v79, v79
	v_fma_f32 v79, v179, v145, -v79
	v_mul_f32_e32 v180, 0.15915494, v104
	v_sin_f32_e32 v107, v79
	v_cos_f32_e32 v106, v79
	v_add_u32_e32 v79, 21, v78
	v_mul_f32_e32 v104, v180, v145
	v_cvt_f32_i32_e32 v79, v79
	v_floor_f32_e32 v104, v104
	v_fma_f32 v104, v180, v145, -v104
	v_sin_f32_e32 v110, v104
	v_cos_f32_e32 v111, v104
	v_add_u32_e32 v104, 22, v78
	v_add_u32_e32 v78, 23, v78
	v_cvt_f32_i32_e32 v104, v104
	v_cvt_f32_i32_e32 v78, v78
	v_mul_f32_e32 v79, 0xbed49a78, v79
	v_exp_f32_e32 v79, v79
	v_mul_f32_e32 v104, 0xbed49a78, v104
	v_mul_f32_e32 v78, 0xbed49a78, v78
	v_exp_f32_e32 v104, v104
	v_exp_f32_e32 v78, v78
	v_mul_f32_e32 v181, 0.15915494, v79
	v_mul_f32_e32 v79, v181, v145
	v_floor_f32_e32 v79, v79
	v_fma_f32 v79, v181, v145, -v79
	v_mul_f32_e32 v182, 0.15915494, v104
	v_mul_f32_e32 v183, 0.15915494, v78
	v_sin_f32_e32 v133, v79
	v_cos_f32_e32 v132, v79
	v_mul_f32_e32 v79, v182, v145
	v_mul_f32_e32 v78, v183, v145
	v_floor_f32_e32 v79, v79
	v_floor_f32_e32 v78, v78
	v_fma_f32 v79, v182, v145, -v79
	v_fma_f32 v78, v183, v145, -v78
	v_sin_f32_e32 v134, v79
	v_cos_f32_e32 v135, v79
	v_sin_f32_e32 v147, v78
	v_cos_f32_e32 v146, v78
	v_pk_mul_f32 v[78:79], v[0:1], v[124:125] op_sel_hi:[0,1]
	v_floor_f32_e32 v100, v100
	v_fma_f32 v101, v178, v145, -v100
	v_sin_f32_e32 v100, v101
	v_cos_f32_e32 v101, v101
	v_pk_mul_f32 v[102:103], v[0:1], v[102:103] op_sel_hi:[0,1]
	v_pk_mul_f32 v[94:95], v[0:1], v[94:95] op_sel_hi:[0,1]
	s_waitcnt vmcnt(2)
; __device__ __forceinline__ unsigned cvtpk(float lo, float hi) { unsigned r; asm volatile("v_cvt_pk_bf16_f32 %0, %1, %2" : "=v"(r) : "v"(lo), "v"(hi)); return r; }
; __device__ __forceinline__ float bflo(unsigned w) { return __uint_as_float(w << 16); }
; __device__ __forceinline__ float bfhi(unsigned w) { return __uint_as_float(w & 0xffff0000u); }
; __device__ __forceinline__ float sin_rev(float rev) { return __builtin_amdgcn_sinf(rev); }
; __device__ __forceinline__ float cos_rev(float rev) { return __builtin_amdgcn_cosf(rev); }
; __device__ __forceinline__ void attn_item(const bf16_t* __restrict__ Qb, const bf16_t* __restrict__ Kh, const bf16_t* __restrict__ Vh, const bf16_t* __restrict__ Zb, ...
;     ...
;     for (int bb = 0; bb < 4; ++bb) { const int d1 = (bb & 1) + 4 * (bb >> 1), d2 = d1 + 2;
;       const float pos = (bb < 2) ? prow : pcol; const float* g1p = qg + d1 * 16 + hq * 8; const float* g2p = qg + d2 * 16 + hq * 8;
;       const f32x4 g1a = *(const f32x4*)g1p, g1b = *(const f32x4*)(g1p + 4), g2a = *(const f32x4*)g2p, g2b = *(const f32x4*)(g2p + 4);
;       float o1[8], o2[8];
; #pragma unroll
;       for (int e = 0; e < 8; ++e) { const unsigned w1 = (e < 2) ? qw[d1].x : (e < 4) ? qw[d1].y : (e < 6) ? qw[d1].z : qw[d1].w, w2 = (e < 2) ? qw[d2].x : (e < 4) ? qw[d2].y : (e < 6) ? qw[d2].z : qw[d2].w;
;         const float x1 = (e & 1) ? bfhi(w1) : bflo(w1), x2 = (e & 1) ? bfhi(w2) : bflo(w2); const float ga = (e < 4) ? g1a[e & 3] : g1b[e & 3], gb = (e < 4) ? g2a[e & 3] : g2b[e & 3];
;         const int fi = (d1 & 1) * 16 + hq * 8 + e; float rev = pos * (__builtin_amdgcn_exp2f(-(float)fi * (13.287712379549449f / 32.0f)) * 0.15915494309189535f); rev -= floorf(rev);
;         const float sn = sin_rev(rev), cs = cos_rev(rev), y1 = x1 * rstd * ga, y2 = x2 * rstd * gb; o1[e] = y1 * cs - y2 * sn; o2[e] = y2 * cs + y1 * sn; }
; #pragma unroll
;       for (int e = 0; e < 8; ++e) qn2 += o1[e] * o1[e] + o2[e] * o2[e];
;       u32x4 p1 = {cvtpk(o1[0], o1[1]), cvtpk(o1[2], o1[3]), cvtpk(o1[4], o1[5]), cvtpk(o1[6], o1[7])}, p2 = {cvtpk(o2[0], o2[1]), cvtpk(o2[2], o2[3]), cvtpk(o2[4], o2[5]), cvtpk(o2[6], o2[7])};
;       qr[d1] = *reinterpret_cast<bf16x8*>(&p1); qr[d2] = *reinterpret_cast<bf16x8*>(&p2); }
	v_mov_b32_e32 v104, v6
	s_waitcnt vmcnt(1)
	v_mov_b32_e32 v105, v10
	v_pk_mul_f32 v[104:105], v[78:79], v[104:105]
	v_mov_b32_e32 v78, v97
	v_mov_b32_e32 v79, v96
	v_mul_f32_e32 v6, v96, v105
	v_pk_fma_f32 v[78:79], v[78:79], v[104:105], v[6:7] op_sel_hi:[1,1,0] neg_lo:[0,0,1] neg_hi:[0,0,1]
	v_mul_f32_e32 v6, v97, v105
	v_pk_fma_f32 v[96:97], v[96:97], v[104:105], v[6:7] op_sel_hi:[1,1,0]
	v_pk_mul_f32 v[104:105], v[0:1], v[116:117] op_sel_hi:[0,1]
	v_mov_b32_e32 v10, v7
	v_pk_mul_f32 v[6:7], v[104:105], v[10:11]
	v_pk_mul_f32 v[76:77], v[0:1], v[76:77] op_sel_hi:[0,1]
	v_mul_f32_e32 v10, v99, v7
	v_pk_fma_f32 v[104:105], v[98:99], v[6:7], v[10:11] op_sel_hi:[1,1,0] neg_lo:[0,0,1] neg_hi:[0,0,1]
	v_mov_b32_e32 v10, v99
	v_mov_b32_e32 v11, v98
	v_mul_f32_e32 v98, v98, v7
	v_pk_fma_f32 v[108:109], v[10:11], v[6:7], v[98:99] op_sel_hi:[1,1,0]
	v_pk_mul_f32 v[6:7], v[0:1], v[112:113] op_sel_hi:[0,1]
	v_mov_b32_e32 v10, v8
	v_mov_b32_e32 v11, v12
	v_pk_mul_f32 v[6:7], v[6:7], v[10:11]
	v_mov_b32_e32 v10, v101
	v_mov_b32_e32 v11, v100
	v_mul_f32_e32 v8, v100, v7
	v_pk_fma_f32 v[112:113], v[10:11], v[6:7], v[8:9] op_sel_hi:[1,1,0] neg_lo:[0,0,1] neg_hi:[0,0,1]
	v_mul_f32_e32 v8, v101, v7
	v_pk_fma_f32 v[116:117], v[100:101], v[6:7], v[8:9] op_sel_hi:[1,1,0]
	v_pk_mul_f32 v[6:7], v[0:1], v[122:123] op_sel_hi:[0,1]
	v_mov_b32_e32 v12, v9
	v_pk_mul_f32 v[6:7], v[6:7], v[12:13]
	v_cvt_pk_bf16_f32 v160, v78, v104
	s_mulk_i32 s0, 0x2080
	v_mul_f32_e32 v8, v107, v7
	v_pk_fma_f32 v[122:123], v[106:107], v[6:7], v[8:9] op_sel_hi:[1,1,0] neg_lo:[0,0,1] neg_hi:[0,0,1]
	v_mov_b32_e32 v8, v107
	v_mov_b32_e32 v9, v106
	v_mul_f32_e32 v10, v106, v7
	v_pk_fma_f32 v[124:125], v[8:9], v[6:7], v[10:11] op_sel_hi:[1,1,0]
	v_pk_mul_f32 v[6:7], v[0:1], v[126:127] op_sel_hi:[0,1]
	v_mov_b32_e32 v8, v2
	s_waitcnt vmcnt(0)
	v_mov_b32_e32 v9, v128
	v_pk_mul_f32 v[6:7], v[6:7], v[8:9]
	v_mov_b32_e32 v8, v111
	v_mov_b32_e32 v9, v110
	v_mul_f32_e32 v2, v110, v7
	v_pk_fma_f32 v[98:99], v[8:9], v[6:7], v[2:3] op_sel_hi:[1,1,0] neg_lo:[0,0,1] neg_hi:[0,0,1]
	v_mul_f32_e32 v2, v111, v7
	v_pk_fma_f32 v[100:101], v[110:111], v[6:7], v[2:3] op_sel_hi:[1,1,0]
	v_pk_mul_f32 v[6:7], v[0:1], v[120:121] op_sel_hi:[0,1]
	v_mov_b32_e32 v128, v3
	v_pk_mul_f32 v[2:3], v[6:7], v[128:129]
	v_cvt_pk_bf16_f32 v161, v112, v122
	v_and_b32_e32 v128, 63, v136
	v_mul_f32_e32 v6, v133, v3
	v_pk_fma_f32 v[106:107], v[132:133], v[2:3], v[6:7] op_sel_hi:[1,1,0] neg_lo:[0,0,1] neg_hi:[0,0,1]
	v_mov_b32_e32 v6, v133
	v_mov_b32_e32 v7, v132
	v_mul_f32_e32 v8, v132, v3
	v_pk_fma_f32 v[110:111], v[6:7], v[2:3], v[8:9] op_sel_hi:[1,1,0]
	v_pk_mul_f32 v[2:3], v[0:1], v[114:115] op_sel_hi:[0,1]
	v_mov_b32_e32 v6, v4
	v_mov_b32_e32 v7, v130
	v_pk_mul_f32 v[2:3], v[2:3], v[6:7]
	v_mov_b32_e32 v6, v135
	v_mov_b32_e32 v7, v134
	v_mul_f32_e32 v4, v134, v3
	v_pk_fma_f32 v[114:115], v[6:7], v[2:3], v[4:5] op_sel_hi:[1,1,0] neg_lo:[0,0,1] neg_hi:[0,0,1]
	v_mul_f32_e32 v4, v135, v3
	v_pk_fma_f32 v[120:121], v[134:135], v[2:3], v[4:5] op_sel_hi:[1,1,0]
	v_pk_mul_f32 v[2:3], v[0:1], v[118:119] op_sel_hi:[0,1]
	v_mov_b32_e32 v130, v5
	v_pk_mul_f32 v[2:3], v[2:3], v[130:131]
	v_cvt_pk_bf16_f32 v162, v98, v106
	v_cvt_f32_ubyte0_e32 v189, v128
	v_mul_f32_e32 v4, v147, v3
	v_pk_fma_f32 v[118:119], v[146:147], v[2:3], v[4:5] op_sel_hi:[1,1,0] neg_lo:[0,0,1] neg_hi:[0,0,1]
	v_mov_b32_e32 v4, v147
	v_mov_b32_e32 v5, v146
	v_mul_f32_e32 v6, v146, v3
	v_pk_fma_f32 v[126:127], v[4:5], v[2:3], v[6:7] op_sel_hi:[1,1,0]
	v_cvt_pk_bf16_f32 v163, v114, v118
	v_cvt_pk_bf16_f32 v156, v96, v108
	v_cvt_pk_bf16_f32 v157, v116, v124
	v_cvt_pk_bf16_f32 v158, v100, v110
	v_mul_f32_e32 v130, v138, v189
	v_cvt_pk_bf16_f32 v159, v120, v126
	global_load_dwordx4 v[2:5], v[14:15], off offset:256
	global_load_dwordx4 v[6:9], v[14:15], off offset:384
	global_load_dwordx4 v[10:13], v[14:15], off offset:272
	global_load_dwordx4 v[164:167], v[14:15], off offset:400
	v_mul_f32_e32 v128, v137, v189
	v_floor_f32_e32 v130, v130
	v_floor_f32_e32 v128, v128
	v_fma_f32 v130, v138, v189, -v130
	v_mul_f32_e32 v138, v142, v189
	v_fma_f32 v129, v137, v189, -v128
	v_floor_f32_e32 v138, v138
	v_sin_f32_e32 v128, v129
	v_cos_f32_e32 v129, v129
	v_fma_f32 v138, v142, v189, -v138
	v_mul_f32_e32 v142, v144, v189
	v_floor_f32_e32 v142, v142
	v_fma_f32 v142, v144, v189, -v142
	v_sin_f32_e32 v131, v130
	v_cos_f32_e32 v130, v130
	v_mul_f32_e32 v132, v139, v189
	v_floor_f32_e32 v132, v132
	v_fma_f32 v133, v139, v189, -v132
	v_sin_f32_e32 v132, v133
	v_cos_f32_e32 v133, v133
	v_mul_f32_e32 v134, v140, v189
	v_floor_f32_e32 v134, v134
	v_fma_f32 v134, v140, v189, -v134
	v_sin_f32_e32 v135, v134
	v_cos_f32_e32 v134, v134
	v_mul_f32_e32 v136, v141, v189
	v_floor_f32_e32 v136, v136
	v_fma_f32 v137, v141, v189, -v136
	v_sin_f32_e32 v136, v137
	v_cos_f32_e32 v137, v137
	v_sin_f32_e32 v139, v138
	v_cos_f32_e32 v138, v138
	v_mul_f32_e32 v140, v143, v189
	v_floor_f32_e32 v140, v140
	v_fma_f32 v141, v143, v189, -v140
	v_sin_f32_e32 v140, v141
	v_cos_f32_e32 v141, v141
	v_sin_f32_e32 v143, v142
	v_cos_f32_e32 v142, v142
	s_add_u32 s0, s42, s0
	s_addc_u32 s1, s43, 0
	v_lshlrev_b32_e32 v206, 3, v186
	s_add_u32 s0, s0, s8
	s_addc_u32 s1, s1, 0
	v_pk_mul_f32 v[38:39], v[38:39], v[38:39]
	v_lshlrev_b32_e32 v221, 8, v187
	v_pk_fma_f32 v[36:37], v[36:37], v[36:37], v[38:39]
	v_pk_mul_f32 v[38:39], v[40:41], v[40:41]
	v_and_b32_e32 v208, 63, v186
	v_pk_fma_f32 v[32:33], v[32:33], v[32:33], v[38:39]
	v_and_b32_e32 v39, 24, v206
	v_pk_add_f32 v[32:33], v[36:37], v[32:33]
	v_pk_mul_f32 v[36:37], v[44:45], v[44:45]
	s_cmp_lg_u32 0, -1
	v_pk_fma_f32 v[36:37], v[42:43], v[42:43], v[36:37]
	s_mul_i32 s9, s6, 0x8200000
	v_pk_add_f32 v[32:33], v[36:37], v[32:33]
	v_pk_mul_f32 v[36:37], v[46:47], v[46:47]
	s_cselect_b32 s6, 0, 0
	v_pk_fma_f32 v[34:35], v[34:35], v[34:35], v[36:37]
	v_lshrrev_b32_e32 v36, 5, v186
	v_pk_add_f32 v[32:33], v[34:35], v[32:33]
	v_pk_mul_f32 v[34:35], v[50:51], v[50:51]
	v_bfe_u32 v37, v206, 5, 2
	v_pk_fma_f32 v[34:35], v[48:49], v[48:49], v[34:35]
	v_and_or_b32 v36, v36, s58, v37
	v_pk_add_f32 v[32:33], v[34:35], v[32:33]
	v_pk_mul_f32 v[34:35], v[54:55], v[54:55]
	v_mov_b32_e32 v244, 1.0
	v_pk_fma_f32 v[34:35], v[52:53], v[52:53], v[34:35]
	s_mov_b32 s76, 0x10000
	v_pk_add_f32 v[32:33], v[34:35], v[32:33]
	v_pk_mul_f32 v[34:35], v[58:59], v[58:59]
	v_pk_mul_f32 v[58:59], v[120:121], v[120:121]
	v_pk_fma_f32 v[34:35], v[56:57], v[56:57], v[34:35]
	s_mov_b32 s77, 0x8000
	s_waitcnt vmcnt(3)
; __device__ __forceinline__ unsigned cvtpk(float lo, float hi) { unsigned r; asm volatile("v_cvt_pk_bf16_f32 %0, %1, %2" : "=v"(r) : "v"(lo), "v"(hi)); return r; }
; __device__ __forceinline__ float bflo(unsigned w) { return __uint_as_float(w << 16); }
; __device__ __forceinline__ float bfhi(unsigned w) { return __uint_as_float(w & 0xffff0000u); }
; __device__ __forceinline__ float sin_rev(float rev) { return __builtin_amdgcn_sinf(rev); }
; __device__ __forceinline__ float cos_rev(float rev) { return __builtin_amdgcn_cosf(rev); }
; __device__ __forceinline__ void attn_item(const bf16_t* __restrict__ Qb, const bf16_t* __restrict__ Kh, const bf16_t* __restrict__ Vh, const bf16_t* __restrict__ Zb, ...
;     ...
;     for (int bb = 0; bb < 4; ++bb) { const int d1 = (bb & 1) + 4 * (bb >> 1), d2 = d1 + 2;
;       const float pos = (bb < 2) ? prow : pcol; const float* g1p = qg + d1 * 16 + hq * 8; const float* g2p = qg + d2 * 16 + hq * 8;
;       const f32x4 g1a = *(const f32x4*)g1p, g1b = *(const f32x4*)(g1p + 4), g2a = *(const f32x4*)g2p, g2b = *(const f32x4*)(g2p + 4);
;       float o1[8], o2[8];
; #pragma unroll
;       for (int e = 0; e < 8; ++e) { const unsigned w1 = (e < 2) ? qw[d1].x : (e < 4) ? qw[d1].y : (e < 6) ? qw[d1].z : qw[d1].w, w2 = (e < 2) ? qw[d2].x : (e < 4) ? qw[d2].y : (e < 6) ? qw[d2].z : qw[d2].w;
;         const float x1 = (e & 1) ? bfhi(w1) : bflo(w1), x2 = (e & 1) ? bfhi(w2) : bflo(w2); const float ga = (e < 4) ? g1a[e & 3] : g1b[e & 3], gb = (e < 4) ? g2a[e & 3] : g2b[e & 3];
;         const int fi = (d1 & 1) * 16 + hq * 8 + e; float rev = pos * (__builtin_amdgcn_exp2f(-(float)fi * (13.287712379549449f / 32.0f)) * 0.15915494309189535f); rev -= floorf(rev);
;         const float sn = sin_rev(rev), cs = cos_rev(rev), y1 = x1 * rstd * ga, y2 = x2 * rstd * gb; o1[e] = y1 * cs - y2 * sn; o2[e] = y2 * cs + y1 * sn; }
; #pragma unroll
;       for (int e = 0; e < 8; ++e) qn2 += o1[e] * o1[e] + o2[e] * o2[e];
;       u32x4 p1 = {cvtpk(o1[0], o1[1]), cvtpk(o1[2], o1[3]), cvtpk(o1[4], o1[5]), cvtpk(o1[6], o1[7])}, p2 = {cvtpk(o2[0], o2[1]), cvtpk(o2[2], o2[3]), cvtpk(o2[4], o2[5]), cvtpk(o2[6], o2[7])};
;       qr[d1] = *reinterpret_cast<bf16x8*>(&p1); qr[d2] = *reinterpret_cast<bf16x8*>(&p2); }
	v_mov_b32_e32 v144, v2
	s_waitcnt vmcnt(2)
	v_mov_b32_e32 v145, v6
	v_pk_mul_f32 v[144:145], v[102:103], v[144:145]
	v_mov_b32_e32 v102, v129
	v_mov_b32_e32 v103, v128
	v_mul_f32_e32 v2, v128, v145
	v_pk_fma_f32 v[102:103], v[102:103], v[144:145], v[2:3] op_sel_hi:[1,1,0] neg_lo:[0,0,1] neg_hi:[0,0,1]
	v_mul_f32_e32 v2, v129, v145
	v_mov_b32_e32 v6, v3
	v_pk_fma_f32 v[128:129], v[128:129], v[144:145], v[2:3] op_sel_hi:[1,1,0]
	v_pk_mul_f32 v[2:3], v[94:95], v[6:7]
	v_mul_f32_e32 v144, v177, v189
	v_mul_f32_e32 v6, v131, v3
	v_pk_fma_f32 v[94:95], v[130:131], v[2:3], v[6:7] op_sel_hi:[1,1,0] neg_lo:[0,0,1] neg_hi:[0,0,1]
	v_mov_b32_e32 v6, v131
	v_mov_b32_e32 v7, v130
	v_mul_f32_e32 v130, v130, v3
	v_pk_fma_f32 v[130:131], v[6:7], v[2:3], v[130:131] op_sel_hi:[1,1,0]
	v_pk_mul_f32 v[2:3], v[0:1], v[92:93] op_sel_hi:[0,1]
	v_mov_b32_e32 v6, v4
	v_mov_b32_e32 v7, v8
	v_pk_mul_f32 v[2:3], v[2:3], v[6:7]
	v_mov_b32_e32 v6, v133
	v_mov_b32_e32 v7, v132
	v_mul_f32_e32 v4, v132, v3
	v_pk_fma_f32 v[92:93], v[6:7], v[2:3], v[4:5] op_sel_hi:[1,1,0] neg_lo:[0,0,1] neg_hi:[0,0,1]
	v_mul_f32_e32 v4, v133, v3
	v_pk_fma_f32 v[132:133], v[132:133], v[2:3], v[4:5] op_sel_hi:[1,1,0]
	v_pk_mul_f32 v[2:3], v[0:1], v[90:91] op_sel_hi:[0,1]
	v_mov_b32_e32 v8, v5
	v_pk_mul_f32 v[2:3], v[2:3], v[8:9]
	v_cvt_pk_bf16_f32 v168, v102, v94
	v_floor_f32_e32 v144, v144
	v_mul_f32_e32 v4, v135, v3
	v_pk_fma_f32 v[90:91], v[134:135], v[2:3], v[4:5] op_sel_hi:[1,1,0] neg_lo:[0,0,1] neg_hi:[0,0,1]
	v_mov_b32_e32 v4, v135
	v_mov_b32_e32 v5, v134
	v_mul_f32_e32 v6, v134, v3
	v_pk_fma_f32 v[134:135], v[4:5], v[2:3], v[6:7] op_sel_hi:[1,1,0]
	v_pk_mul_f32 v[2:3], v[0:1], v[88:89] op_sel_hi:[0,1]
	s_waitcnt vmcnt(1)
	v_mov_b32_e32 v4, v10
	s_waitcnt vmcnt(0)
	v_mov_b32_e32 v5, v164
	v_pk_mul_f32 v[2:3], v[2:3], v[4:5]
	v_mov_b32_e32 v4, v137
	v_mov_b32_e32 v5, v136
	v_mul_f32_e32 v6, v136, v3
	v_pk_fma_f32 v[88:89], v[4:5], v[2:3], v[6:7] op_sel_hi:[1,1,0] neg_lo:[0,0,1] neg_hi:[0,0,1]
	v_mul_f32_e32 v4, v137, v3
	v_pk_fma_f32 v[136:137], v[136:137], v[2:3], v[4:5] op_sel_hi:[1,1,0]
	v_pk_mul_f32 v[2:3], v[0:1], v[86:87] op_sel_hi:[0,1]
	v_mov_b32_e32 v164, v11
	v_pk_mul_f32 v[2:3], v[2:3], v[164:165]
	v_cvt_pk_bf16_f32 v169, v92, v90
	v_fma_f32 v144, v177, v189, -v144
	v_mul_f32_e32 v4, v139, v3
	v_pk_fma_f32 v[86:87], v[138:139], v[2:3], v[4:5] op_sel_hi:[1,1,0] neg_lo:[0,0,1] neg_hi:[0,0,1]
	v_mov_b32_e32 v4, v139
	v_mov_b32_e32 v5, v138
	v_mul_f32_e32 v6, v138, v3
	v_pk_fma_f32 v[138:139], v[4:5], v[2:3], v[6:7] op_sel_hi:[1,1,0]
	v_pk_mul_f32 v[2:3], v[0:1], v[84:85] op_sel_hi:[0,1]
	v_mov_b32_e32 v4, v12
	v_mov_b32_e32 v5, v166
	v_pk_mul_f32 v[2:3], v[2:3], v[4:5]
	v_mov_b32_e32 v4, v141
	v_mov_b32_e32 v5, v140
	v_mul_f32_e32 v6, v140, v3
	v_pk_fma_f32 v[84:85], v[4:5], v[2:3], v[6:7] op_sel_hi:[1,1,0] neg_lo:[0,0,1] neg_hi:[0,0,1]
	v_mul_f32_e32 v4, v141, v3
	v_pk_fma_f32 v[140:141], v[140:141], v[2:3], v[4:5] op_sel_hi:[1,1,0]
	v_pk_mul_f32 v[2:3], v[0:1], v[80:81] op_sel_hi:[0,1]
	v_mov_b32_e32 v166, v13
	v_pk_mul_f32 v[2:3], v[2:3], v[166:167]
	v_cvt_pk_bf16_f32 v170, v88, v86
	v_sin_f32_e32 v147, v144
	v_mul_f32_e32 v4, v143, v3
	v_pk_fma_f32 v[80:81], v[142:143], v[2:3], v[4:5] op_sel_hi:[1,1,0] neg_lo:[0,0,1] neg_hi:[0,0,1]
	v_mov_b32_e32 v4, v143
	v_mov_b32_e32 v5, v142
	v_mul_f32_e32 v6, v142, v3
	v_pk_fma_f32 v[142:143], v[4:5], v[2:3], v[6:7] op_sel_hi:[1,1,0]
	v_cvt_pk_bf16_f32 v171, v84, v80
	v_cvt_pk_bf16_f32 v164, v128, v130
	v_cvt_pk_bf16_f32 v165, v132, v134
	v_cvt_pk_bf16_f32 v166, v136, v138
	v_cos_f32_e32 v146, v144
	v_cvt_pk_bf16_f32 v167, v140, v142
	global_load_dwordx4 v[2:5], v[14:15], off offset:320
	global_load_dwordx4 v[6:9], v[14:15], off offset:448
	global_load_dwordx4 v[10:13], v[14:15], off offset:336
	global_load_dwordx4 v[172:175], v[14:15], off offset:464
	v_mul_f32_e32 v144, v178, v189
	v_mul_f32_e32 v14, v176, v189
	v_floor_f32_e32 v144, v144
	v_floor_f32_e32 v14, v14
	v_fma_f32 v144, v178, v189, -v144
	v_fma_f32 v15, v176, v189, -v14
	v_sin_f32_e32 v176, v144
	v_cos_f32_e32 v177, v144
	v_mul_f32_e32 v144, v179, v189
	v_floor_f32_e32 v144, v144
	v_fma_f32 v144, v179, v189, -v144
	v_sin_f32_e32 v179, v144
	v_cos_f32_e32 v178, v144
	v_mul_f32_e32 v144, v180, v189
	v_floor_f32_e32 v144, v144
	v_fma_f32 v144, v180, v189, -v144
	v_sin_f32_e32 v184, v144
	v_cos_f32_e32 v185, v144
	v_mul_f32_e32 v144, v181, v189
	v_floor_f32_e32 v144, v144
	v_fma_f32 v144, v181, v189, -v144
	v_sin_f32_e32 v191, v144
	v_cos_f32_e32 v190, v144
	v_mul_f32_e32 v144, v182, v189
	v_floor_f32_e32 v144, v144
	v_fma_f32 v144, v182, v189, -v144
	v_sin_f32_e32 v192, v144
	v_cos_f32_e32 v193, v144
	v_mul_f32_e32 v144, v183, v189
	v_sin_f32_e32 v14, v15
	v_cos_f32_e32 v15, v15
	v_floor_f32_e32 v144, v144
	v_fma_f32 v144, v183, v189, -v144
	v_sin_f32_e32 v195, v144
	v_cos_f32_e32 v194, v144
	v_ashrrev_i32_e32 v189, 4, v186
	v_add_u32_e32 v207, 32, v189
	v_pk_add_f32 v[32:33], v[34:35], v[32:33]
	v_pk_mul_f32 v[34:35], v[82:83], v[82:83]
	v_lshlrev_b32_e32 v38, 5, v189
	v_pk_fma_f32 v[34:35], v[64:65], v[64:65], v[34:35]
	v_and_or_b32 v38, v38, s59, v39
	v_pk_add_f32 v[32:33], v[34:35], v[32:33]
	v_pk_mul_f32 v[34:35], v[96:97], v[96:97]
	v_lshlrev_b32_e32 v38, 1, v38
	v_pk_fma_f32 v[34:35], v[78:79], v[78:79], v[34:35]
	v_lshl_or_b32 v228, v36, 9, v38
	v_pk_add_f32 v[32:33], v[34:35], v[32:33]
	v_pk_mul_f32 v[34:35], v[108:109], v[108:109]
	v_lshrrev_b32_e32 v36, 1, v207
	v_pk_fma_f32 v[34:35], v[104:105], v[104:105], v[34:35]
	v_and_or_b32 v36, v36, s58, v37
	v_lshlrev_b32_e32 v82, 4, v186
	v_add_u32_e32 v108, 0, v228
	v_pk_add_f32 v[32:33], v[34:35], v[32:33]
	v_pk_mul_f32 v[34:35], v[116:117], v[116:117]
	v_lshl_or_b32 v229, v36, 9, v38
	v_lshlrev_b32_e32 v36, 8, v189
	v_and_b32_e32 v38, 0xf0, v186
	v_lshlrev_b32_e32 v39, 8, v207
	v_pk_fma_f32 v[34:35], v[112:113], v[112:113], v[34:35]
	v_add_u32_e32 v83, 0, v221
	v_pk_add_f32 v[32:33], v[34:35], v[32:33]
	v_pk_mul_f32 v[34:35], v[124:125], v[124:125]
	v_add_u32_e32 v109, 0, v229
	v_pk_fma_f32 v[34:35], v[122:123], v[122:123], v[34:35]
	v_pk_mul_f32 v[78:79], v[126:127], v[126:127]
	v_pk_add_f32 v[32:33], v[34:35], v[32:33]
	v_pk_mul_f32 v[34:35], v[100:101], v[100:101]
	s_mov_b32 s78, -1
	v_pk_fma_f32 v[34:35], v[98:99], v[98:99], v[34:35]
	v_mov_b32_e32 v219, 0
	v_pk_add_f32 v[32:33], v[34:35], v[32:33]
	v_pk_mul_f32 v[34:35], v[110:111], v[110:111]
	s_waitcnt vmcnt(3)
; __device__ __forceinline__ unsigned cvtpk(float lo, float hi) { unsigned r; asm volatile("v_cvt_pk_bf16_f32 %0, %1, %2" : "=v"(r) : "v"(lo), "v"(hi)); return r; }
; __device__ __forceinline__ void attn_item(const bf16_t* __restrict__ Qb, const bf16_t* __restrict__ Kh, const bf16_t* __restrict__ Vh, const bf16_t* __restrict__ Zb, ...
;     ...
;     for (int bb = 0; bb < 4; ++bb) { const int d1 = (bb & 1) + 4 * (bb >> 1), d2 = d1 + 2;
;       const float pos = (bb < 2) ? prow : pcol; const float* g1p = qg + d1 * 16 + hq * 8; const float* g2p = qg + d2 * 16 + hq * 8;
;       const f32x4 g1a = *(const f32x4*)g1p, g1b = *(const f32x4*)(g1p + 4), g2a = *(const f32x4*)g2p, g2b = *(const f32x4*)(g2p + 4);
;       float o1[8], o2[8];
; #pragma unroll
;       for (int e = 0; e < 8; ++e) { const unsigned w1 = (e < 2) ? qw[d1].x : (e < 4) ? qw[d1].y : (e < 6) ? qw[d1].z : qw[d1].w, w2 = (e < 2) ? qw[d2].x : (e < 4) ? qw[d2].y : (e < 6) ? qw[d2].z : qw[d2].w;
;         const float x1 = (e & 1) ? bfhi(w1) : bflo(w1), x2 = (e & 1) ? bfhi(w2) : bflo(w2); const float ga = (e < 4) ? g1a[e & 3] : g1b[e & 3], gb = (e < 4) ? g2a[e & 3] : g2b[e & 3];
;         const int fi = (d1 & 1) * 16 + hq * 8 + e; float rev = pos * (__builtin_amdgcn_exp2f(-(float)fi * (13.287712379549449f / 32.0f)) * 0.15915494309189535f); rev -= floorf(rev);
;         const float sn = sin_rev(rev), cs = cos_rev(rev), y1 = x1 * rstd * ga, y2 = x2 * rstd * gb; o1[e] = y1 * cs - y2 * sn; o2[e] = y2 * cs + y1 * sn; }
; #pragma unroll
;       for (int e = 0; e < 8; ++e) qn2 += o1[e] * o1[e] + o2[e] * o2[e];
;       u32x4 p1 = {cvtpk(o1[0], o1[1]), cvtpk(o1[2], o1[3]), cvtpk(o1[4], o1[5]), cvtpk(o1[6], o1[7])}, p2 = {cvtpk(o2[0], o2[1]), cvtpk(o2[2], o2[3]), cvtpk(o2[4], o2[5]), cvtpk(o2[6], o2[7])};
;       qr[d1] = *reinterpret_cast<bf16x8*>(&p1); qr[d2] = *reinterpret_cast<bf16x8*>(&p2); }
;     ...
;   const int sr = tid >> 4, sc = (tid & 15) * 8, vst0 = v_st_nat(sr, sc), vst1 = v_st_nat(32 + sr, sc), kst0 = KOFF + KSWZ(sr, sc * 2), kst1 = KOFF + KSWZ(32 + sr, sc * 2);
;   const int vb0 = (int)(uintptr_t)lds + v_rd_base(lane);
;   struct { bf16x8 vs0, vs1, ks0, ks1; } sr_;
;     ...
;   f32x16 pA0, pA1, pB0, pB1; float alA, alB; VF8 vfa; bf16x8 pa0, pa1, pa2, pa3; const int NT = seq / KVBLK;
;   int s_prev = 0, s_cur = SLOT, s_next = 2 * SLOT;
;   SLOAD(0); SWAIT(); SWRITE(0); __syncthreads();
	v_mov_b32_e32 v144, v2
	s_waitcnt vmcnt(2)
	v_mov_b32_e32 v145, v6
	v_pk_mul_f32 v[144:145], v[76:77], v[144:145]
	v_mov_b32_e32 v76, v15
	v_mov_b32_e32 v77, v14
	v_mul_f32_e32 v2, v14, v145
	v_pk_fma_f32 v[76:77], v[76:77], v[144:145], v[2:3] op_sel_hi:[1,1,0] neg_lo:[0,0,1] neg_hi:[0,0,1]
	v_mul_f32_e32 v2, v15, v145
	v_pk_fma_f32 v[144:145], v[14:15], v[144:145], v[2:3] op_sel_hi:[1,1,0]
	v_pk_mul_f32 v[14:15], v[0:1], v[60:61] op_sel_hi:[0,1]
	v_mov_b32_e32 v6, v3
	v_pk_mul_f32 v[2:3], v[14:15], v[6:7]
	v_pk_fma_f32 v[34:35], v[106:107], v[106:107], v[34:35]
	v_mul_f32_e32 v6, v147, v3
	v_pk_fma_f32 v[60:61], v[146:147], v[2:3], v[6:7] op_sel_hi:[1,1,0] neg_lo:[0,0,1] neg_hi:[0,0,1]
	v_mov_b32_e32 v6, v147
	v_mov_b32_e32 v7, v146
	v_mul_f32_e32 v14, v146, v3
	v_pk_fma_f32 v[146:147], v[6:7], v[2:3], v[14:15] op_sel_hi:[1,1,0]
	v_pk_mul_f32 v[2:3], v[0:1], v[74:75] op_sel_hi:[0,1]
	v_mov_b32_e32 v6, v4
	v_mov_b32_e32 v7, v8
	v_pk_mul_f32 v[2:3], v[2:3], v[6:7]
	v_mov_b32_e32 v6, v177
	v_mov_b32_e32 v7, v176
	v_mul_f32_e32 v4, v176, v3
	v_pk_fma_f32 v[74:75], v[6:7], v[2:3], v[4:5] op_sel_hi:[1,1,0] neg_lo:[0,0,1] neg_hi:[0,0,1]
	v_mul_f32_e32 v4, v177, v3
	v_pk_fma_f32 v[180:181], v[176:177], v[2:3], v[4:5] op_sel_hi:[1,1,0]
	v_pk_mul_f32 v[2:3], v[0:1], v[66:67] op_sel_hi:[0,1]
	v_mov_b32_e32 v8, v5
	v_pk_mul_f32 v[2:3], v[2:3], v[8:9]
	s_waitcnt vmcnt(0)
	v_mov_b32_e32 v15, v174
	v_mul_f32_e32 v4, v179, v3
	v_pk_fma_f32 v[66:67], v[178:179], v[2:3], v[4:5] op_sel_hi:[1,1,0] neg_lo:[0,0,1] neg_hi:[0,0,1]
	v_mov_b32_e32 v4, v179
	v_mov_b32_e32 v5, v178
	v_mul_f32_e32 v6, v178, v3
	v_pk_fma_f32 v[182:183], v[4:5], v[2:3], v[6:7] op_sel_hi:[1,1,0]
	v_pk_mul_f32 v[2:3], v[0:1], v[72:73] op_sel_hi:[0,1]
	v_mov_b32_e32 v4, v10
	v_mov_b32_e32 v5, v172
	v_pk_mul_f32 v[6:7], v[0:1], v[62:63] op_sel_hi:[0,1]
	v_mov_b32_e32 v172, v11
	v_pk_mul_f32 v[2:3], v[2:3], v[4:5]
	v_mov_b32_e32 v4, v185
	v_mov_b32_e32 v5, v184
	v_pk_mul_f32 v[6:7], v[6:7], v[172:173]
	v_mov_b32_e32 v10, v191
	v_mov_b32_e32 v11, v190
	v_pk_mul_f32 v[62:63], v[0:1], v[70:71] op_sel_hi:[0,1]
	v_mov_b32_e32 v174, v13
	v_pk_mul_f32 v[4:5], v[4:5], v[2:3]
	v_pk_mul_f32 v[8:9], v[190:191], v[6:7]
	v_pk_mul_f32 v[6:7], v[10:11], v[6:7]
	v_pk_mul_f32 v[10:11], v[0:1], v[68:69] op_sel_hi:[0,1]
	v_mov_b32_e32 v14, v12
	v_pk_mul_f32 v[12:13], v[62:63], v[174:175]
	v_mov_b32_e32 v62, v195
	v_mov_b32_e32 v63, v194
	v_pk_mul_f32 v[2:3], v[184:185], v[2:3]
	v_pk_mul_f32 v[10:11], v[10:11], v[14:15]
	v_mov_b32_e32 v14, v193
	v_mov_b32_e32 v15, v192
	v_pk_mul_f32 v[68:69], v[194:195], v[12:13]
	v_pk_mul_f32 v[12:13], v[62:63], v[12:13]
	v_mov_b32_e32 v62, v8
	v_mov_b32_e32 v63, v4
	v_mov_b32_e32 v4, v9
	v_pk_mul_f32 v[14:15], v[14:15], v[10:11]
	v_pk_add_f32 v[62:63], v[62:63], v[4:5] neg_lo:[0,1] neg_hi:[0,1]
	v_mov_b32_e32 v4, v6
	v_mov_b32_e32 v5, v2
	v_mov_b32_e32 v2, v7
	v_pk_mul_f32 v[10:11], v[192:193], v[10:11]
	v_pk_add_f32 v[72:73], v[4:5], v[2:3]
	v_mov_b32_e32 v2, v68
	v_mov_b32_e32 v3, v14
	v_mov_b32_e32 v14, v69
	v_pk_add_f32 v[68:69], v[2:3], v[14:15] neg_lo:[0,1] neg_hi:[0,1]
	v_mov_b32_e32 v2, v12
	v_mov_b32_e32 v3, v10
	v_mov_b32_e32 v10, v13
	v_and_b32_e32 v70, 0x78, v206
	v_mov_b32_e32 v71, v1
	v_pk_add_f32 v[184:185], v[2:3], v[10:11]
	v_mad_i64_i32 v[2:3], s[36:37], v189, s61, v[70:71]
	v_lshl_add_u64 v[2:3], v[2:3], 1, s[0:1]
	v_cvt_pk_bf16_f32 v176, v76, v60
	v_cvt_pk_bf16_f32 v177, v74, v66
	v_cvt_pk_bf16_f32 v178, v63, v62
	v_cvt_pk_bf16_f32 v179, v69, v68
	v_cvt_pk_bf16_f32 v172, v144, v146
	v_cvt_pk_bf16_f32 v173, v180, v182
	v_cvt_pk_bf16_f32 v174, v73, v72
	v_cvt_pk_bf16_f32 v175, v185, v184
	global_load_dwordx4 v[190:193], v[2:3], off offset:2560
	v_mad_i64_i32 v[4:5], s[36:37], v207, s61, v[70:71]
	v_lshl_add_u64 v[4:5], v[4:5], 1, s[0:1]
	global_load_dwordx4 v[194:197], v[4:5], off offset:2560
	global_load_dwordx4 v[198:201], v[2:3], off offset:2048
	global_load_dwordx4 v[202:205], v[4:5], off offset:2048
	v_lshlrev_b32_e32 v37, 1, v70
	s_waitcnt vmcnt(0)
	v_bitop3_b32 v231, v37, v36, v38 bitop3:0xde
	v_bitop3_b32 v232, v39, v37, v38 bitop3:0xf6
	v_add_u32_e32 v112, 0, v231
	v_add_u32_e32 v113, 0, v232
	v_pk_add_f32 v[56:57], v[34:35], v[32:33]
	v_and_b32_e32 v0, 0x3fffffc0, v186
	v_mov_b32_e32 v14, v1
	v_mov_b32_e32 v15, v1
	v_lshl_add_u32 v213, v0, 2, s56
	v_mov_b32_e32 v0, v1
	v_mov_b32_e32 v2, v1
	v_mov_b32_e32 v3, v1
	v_mov_b32_e32 v4, v1
	v_mov_b32_e32 v5, v1
	v_mov_b32_e32 v6, v1
	v_mov_b32_e32 v7, v1
	v_mov_b32_e32 v8, v1
	v_mov_b32_e32 v9, v1
	v_mov_b32_e32 v10, v1
	v_mov_b32_e32 v11, v1
	v_mov_b32_e32 v12, v1
	v_mov_b32_e32 v13, v1
	v_or_b32_e32 v106, 0xc0, v212
	v_or_b32_e32 v107, 0xe0, v212
	v_lshl_add_u32 v220, v187, 2, v213
	s_waitcnt vmcnt(3)
	ds_write_b128 v108, v[190:193]
	v_and_b32_e32 v190, 0xf0, v82
	v_bitop3_b32 v234, v188, v190, 16 bitop3:0x6c
	v_add_u32_e32 v36, v83, v234
	s_waitcnt vmcnt(2)
	ds_write_b128 v109, v[194:197]
	s_waitcnt vmcnt(1)
	ds_write_b128 v112, v[198:201] offset:16384
	s_waitcnt vmcnt(0)
	ds_write_b128 v113, v[202:205] offset:16384
	s_waitcnt lgkmcnt(0)
	s_barrier
; #define SLOAD(k0) do { sr_.vs0 = *(const bf16x8*)(&Vh[(long)((k0) + sr) * LDK + sc]); sr_.vs1 = *(const bf16x8*)(&Vh[(long)((k0) + 32 + sr) * LDK + sc]); \
;     sr_.ks0 = *(const bf16x8*)(&Kh[(long)((k0) + sr) * LDK + sc]); sr_.ks1 = *(const bf16x8*)(&Kh[(long)((k0) + 32 + sr) * LDK + sc]); } while (0)
; __device__ __forceinline__ void qkt(f32x16& p0, f32x16& p1, const bf16_t* Ks, const bf16x8* qr, const f32x16& negm, int r32, int hi) {
; #pragma unroll
;   for (int d0 = 0; d0 < 8; ++d0) { int cb = (d0 * 16 + hi * 8) * 2;
;     bf16x8 b0 = *reinterpret_cast<const bf16x8*>((const char*)Ks + KSWZ(r32, cb));
;     bf16x8 b1 = *reinterpret_cast<const bf16x8*>((const char*)Ks + KSWZ(32 + r32, cb));
;     if (d0 == 0) { p0 = __builtin_amdgcn_mfma_f32_32x32x16_bf16(b0, qr[0], negm, 0, 0, 0); p1 = __builtin_amdgcn_mfma_f32_32x32x16_bf16(b1, qr[0], negm, 0, 0, 0); }
;     else { p0 = __builtin_amdgcn_mfma_f32_32x32x16_bf16(b0, qr[d0], p0, 0, 0, 0); p1 = __builtin_amdgcn_mfma_f32_32x32x16_bf16(b1, qr[d0], p1, 0, 0, 0); } }
; }
; __device__ __forceinline__ void attn_item(const bf16_t* __restrict__ Qb, const bf16_t* __restrict__ Kh, const bf16_t* __restrict__ Vh, const bf16_t* __restrict__ Zb, ...
;     ...
;   SLOAD(KVBLK);
;   qkt(pA0, pA1, (const bf16_t*)(lds + KOFF), qr, negm, r32, hi); partialSM<true>(pA0, pA1, m_reg, negm, alA);
	ds_read_b128 v[48:51], v36 offset:24576
	ds_read_b128 v[52:55], v36 offset:16384
	s_waitcnt lgkmcnt(0)
	v_mfma_f32_32x32x16_bf16 v[32:47], v[52:55], v[152:155], v[16:31]
	v_fma_f32 v52, v114, v114, v58
	v_fma_f32 v53, v115, v115, v59
	v_bitop3_b32 v233, v212, v190, 32 bitop3:0x36
	v_add_f32_e64 v64, v52, v56
	v_add_f32_e64 v65, v53, v57
	v_add_u32_e32 v56, v83, v233
	ds_read_b128 v[52:55], v56 offset:24576
	ds_read_b128 v[56:59], v56 offset:16384
	v_bitop3_b32 v230, v212, v190, 64 bitop3:0x36
	v_bitop3_b32 v227, v212, v190, s62 bitop3:0x36
	v_mfma_f32_32x32x16_bf16 v[16:31], v[48:51], v[152:155], v[16:31]
	v_fma_f32 v48, v118, v118, v78
	v_fma_f32 v49, v119, v119, v79
	v_mul_f32_e64 v50, v128, v128
	v_mul_f32_e64 v51, v129, v129
	v_add_f32_e64 v48, v48, v64
	v_add_f32_e64 v49, v49, v65
	v_pk_fma_f32 v[50:51], v[102:103], v[102:103], v[50:51]
	v_bitop3_b32 v226, v212, v190, s63 bitop3:0x36
	v_pk_add_f32 v[48:49], v[48:49], v[50:51]
	v_pk_mul_f32 v[50:51], v[130:131], v[130:131]
	s_waitcnt lgkmcnt(0)
	v_mfma_f32_32x32x16_bf16 v[32:47], v[56:59], v[160:163], v[32:47]
	v_fma_f32 v50, v94, v94, v50
	v_fma_f32 v51, v95, v95, v51
	v_add_u32_e32 v56, v83, v230
	v_add_f32_e64 v64, v50, v48
	v_add_f32_e64 v65, v51, v49
	v_pk_mul_f32 v[48:49], v[132:133], v[132:133]
	v_bitop3_b32 v225, v212, v190, s64 bitop3:0x36
	v_pk_fma_f32 v[78:79], v[92:93], v[92:93], v[48:49]
	ds_read_b128 v[48:51], v56 offset:24576
	ds_read_b128 v[56:59], v56 offset:16384
	v_mfma_f32_32x32x16_bf16 v[16:31], v[52:55], v[160:163], v[16:31]
	v_mul_f32_e64 v54, v134, v134
	v_mul_f32_e64 v55, v135, v135
	v_add_f32_e64 v52, v78, v64
	v_add_f32_e64 v53, v79, v65
	v_fma_f32 v54, v90, v90, v54
	v_fma_f32 v55, v91, v91, v55
	v_bitop3_b32 v224, v212, v190, s60 bitop3:0x36
	v_pk_add_f32 v[52:53], v[54:55], v[52:53]
	v_pk_mul_f32 v[54:55], v[136:137], v[136:137]
	v_bitop3_b32 v223, v212, v190, s59 bitop3:0x36
	v_pk_fma_f32 v[54:55], v[88:89], v[88:89], v[54:55]
	s_waitcnt lgkmcnt(0)
	v_mfma_f32_32x32x16_bf16 v[32:47], v[56:59], v[148:151], v[32:47]
	v_add_f32_e64 v52, v54, v52
	v_add_f32_e64 v53, v55, v53
	v_mul_f32_e64 v54, v138, v138
	v_mul_f32_e64 v55, v139, v139
	v_add_u32_e32 v56, v83, v227
	v_pk_fma_f32 v[54:55], v[86:87], v[86:87], v[54:55]
	v_bitop3_b32 v236, v212, v221, v190 bitop3:0xde
	v_pk_add_f32 v[64:65], v[54:55], v[52:53]
	ds_read_b128 v[52:55], v56 offset:24576
	ds_read_b128 v[56:59], v56 offset:16384
	v_mfma_f32_32x32x16_bf16 v[16:31], v[48:51], v[148:151], v[16:31]
	v_mul_f32_e64 v48, v140, v140
	v_mul_f32_e64 v49, v141, v141
	v_mul_f32_e64 v50, v142, v142
	v_mul_f32_e64 v51, v143, v143
	v_fma_f32 v48, v84, v84, v48
	v_fma_f32 v49, v85, v85, v49
	v_pk_fma_f32 v[50:51], v[80:81], v[80:81], v[50:51]
	v_pk_add_f32 v[48:49], v[48:49], v[64:65]
	v_bitop3_b32 v242, v106, v221, v190 bitop3:0xde
	v_pk_add_f32 v[48:49], v[50:51], v[48:49]
	s_waitcnt lgkmcnt(0)
	v_mfma_f32_32x32x16_bf16 v[32:47], v[56:59], v[156:159], v[32:47]
	v_mul_f32_e64 v50, v144, v144
	v_mul_f32_e64 v51, v145, v145
	v_add_u32_e32 v56, v83, v226
	v_fma_f32 v50, v76, v76, v50
	v_fma_f32 v51, v77, v77, v51
	v_pk_mul_f32 v[76:77], v[146:147], v[146:147]
	v_pk_add_f32 v[64:65], v[48:49], v[50:51]
	ds_read_b128 v[48:51], v56 offset:24576
	ds_read_b128 v[56:59], v56 offset:16384
	v_bitop3_b32 v243, v107, v221, v190 bitop3:0xde
	v_mfma_f32_32x32x16_bf16 v[16:31], v[52:55], v[156:159], v[16:31]
	v_fma_f32 v52, v60, v60, v76
	v_fma_f32 v53, v61, v61, v77
	v_mul_f32_e64 v54, v180, v180
	v_mul_f32_e64 v55, v181, v181
	v_add_f32_e64 v52, v52, v64
	v_add_f32_e64 v53, v53, v65
	v_pk_fma_f32 v[54:55], v[74:75], v[74:75], v[54:55]
	s_nop 0
	v_pk_add_f32 v[52:53], v[54:55], v[52:53]
	v_pk_mul_f32 v[54:55], v[182:183], v[182:183]
	s_waitcnt lgkmcnt(0)
	v_mfma_f32_32x32x16_bf16 v[32:47], v[56:59], v[168:171], v[32:47]
	v_fma_f32 v54, v66, v66, v54
	v_fma_f32 v55, v67, v67, v55
	v_add_u32_e32 v56, v83, v225
	v_add_f32_e64 v60, v54, v52
	v_add_f32_e64 v61, v55, v53
	v_pk_mul_f32 v[52:53], v[72:73], v[72:73]
	s_nop 0
	v_pk_fma_f32 v[62:63], v[62:63], v[62:63], v[52:53]
	ds_read_b128 v[52:55], v56 offset:24576
	ds_read_b128 v[56:59], v56 offset:16384
	v_mfma_f32_32x32x16_bf16 v[16:31], v[48:51], v[168:171], v[16:31]
	v_add_f32_e64 v48, v63, v60
	v_add_f32_e64 v49, v62, v61
	v_mul_f32_e64 v50, v184, v184
	v_mul_f32_e64 v51, v185, v185
	v_add_f32_e64 v48, v62, v48
	v_add_f32_e64 v49, v63, v49
	v_pk_fma_f32 v[50:51], v[68:69], v[68:69], v[50:51]
	v_lshlrev_b32_e32 v60, 3, v208
	v_pk_add_f32 v[48:49], v[50:51], v[48:49] op_sel:[1,0] op_sel_hi:[0,1]
	v_pk_add_f32 v[64:65], v[50:51], v[48:49]
	s_waitcnt lgkmcnt(0)
	v_mfma_f32_32x32x16_bf16 v[32:47], v[56:59], v[176:179], v[32:47]
	v_and_b32_e32 v48, 0xc0, v82
	v_add_u32_e32 v56, v83, v224
	v_and_or_b32 v61, v60, 24, v48
	v_lshlrev_b32_e32 v62, 1, v186
	ds_read_b128 v[48:51], v56 offset:24576
	ds_read_b128 v[56:59], v56 offset:16384
	v_or_b32_e32 v65, 0xa0, v212
	v_bitop3_b32 v241, v65, v221, v190 bitop3:0xde
	v_mfma_f32_32x32x16_bf16 v[16:31], v[52:55], v[176:179], v[16:31]
	v_and_b32_e32 v52, 32, v62
	v_and_b32_e32 v53, 0x100, v60
	v_or3_b32 v52, v61, v52, v53
	v_add_u32_e32 v235, s6, v52
	v_add_u32_e32 v52, 64, v189
	v_mad_i64_i32 v[52:53], s[6:7], v52, s61, v[70:71]
	v_add_u32_e32 v62, 0x60, v189
	s_waitcnt lgkmcnt(0)
	v_mfma_f32_32x32x16_bf16 v[32:47], v[56:59], v[164:167], v[32:47]
	v_lshl_add_u64 v[60:61], v[52:53], 1, s[0:1]
	v_add_u32_e32 v56, v83, v223
	ds_read_b128 v[52:55], v56 offset:24576
	ds_read_b128 v[56:59], v56 offset:16384
	v_mfma_f32_32x32x16_bf16 v[16:31], v[48:51], v[164:167], v[16:31]
	v_mad_i64_i32 v[48:49], s[6:7], v62, s61, v[70:71]
	v_lshl_add_u64 v[66:67], v[48:49], 1, s[0:1]
	global_load_dwordx4 v[48:51], v[60:61], off offset:2560
	s_nop 0
	global_load_dwordx4 v[60:63], v[60:61], off offset:2048
	s_nop 0
	global_load_dwordx4 v[98:101], v[66:67], off offset:2560
	global_load_dwordx4 v[102:105], v[66:67], off offset:2048
	v_cmp_gt_u32_e64 s[6:7], 32, v208
	s_waitcnt lgkmcnt(0)
; template <bool FIRST, bool DOEXP = true>
; __device__ __forceinline__ void partialSM(f32x16& p0, f32x16& p1, float& m_reg, f32x16& negm, float& alpha, const bool track = true) {
;     ...
;   float pmax = p0[0];
; #pragma unroll
;   for (int r = 1; r < 16; ++r) pmax = fmaxf(pmax, p0[r]);
; #pragma unroll
;   for (int r = 0; r < 16; ++r) pmax = fmaxf(pmax, p1[r]);
;   { auto rr = __builtin_amdgcn_permlane32_swap(__float_as_uint(pmax), __float_as_uint(pmax), false, false);
;     pmax = fmaxf(__uint_as_float(rr[0]), __uint_as_float(rr[1])); }
;   if (!FIRST && __builtin_expect(__all(pmax <= THRL), 1)) { alpha = 1.f; }
;   else { const float dl = FIRST ? pmax : fmaxf(pmax, 0.f); m_reg += dl; alpha = FIRST ? 1.f : __builtin_amdgcn_exp2f(-dl);
; #pragma unroll
;     for (int r = 0; r < 16; ++r) { p0[r] -= dl; p1[r] -= dl; }
; #pragma unroll
;     for (int r = 0; r < 16; ++r) negm[r] = -m_reg;
;     asm volatile("" : "+v"(negm)); }
;   if (DOEXP) {
; #pragma unroll
;     for (int r = 0; r < 16; ++r) p0[r] = __builtin_amdgcn_exp2f(p0[r]); }
; __device__ __forceinline__ void attn_item(const bf16_t* __restrict__ Qb, const bf16_t* __restrict__ Kh, const bf16_t* __restrict__ Vh, const bf16_t* __restrict__ Zb, ...
;     ...
;   { auto rr = __builtin_amdgcn_permlane32_swap(__float_as_uint(qn2), __float_as_uint(qn2), false, false); qn2 = __uint_as_float(rr[0]) + __uint_as_float(rr[1]); }
;   const bool track = !__all(__builtin_sqrtf(qn2) * kmaxg - m_reg <= 90.f);
	v_mfma_f32_32x32x16_bf16 v[32:47], v[56:59], v[172:175], v[32:47]
	v_or_b32_e32 v56, 32, v212
	v_or_b32_e32 v57, 64, v212
	v_or_b32_e32 v58, 0x60, v212
	v_or_b32_e32 v59, 0x80, v212
	v_bitop3_b32 v237, v56, v221, v190 bitop3:0xde
	v_bitop3_b32 v238, v57, v221, v190 bitop3:0xde
	v_bitop3_b32 v239, v58, v221, v190 bitop3:0xde
	v_mfma_f32_32x32x16_bf16 v[16:31], v[52:55], v[172:175], v[16:31]
	s_nop 3
	v_max_f32_e32 v52, v33, v33
	v_max_f32_e32 v53, v32, v32
	v_max_f32_e32 v52, v53, v52
	v_max3_f32 v52, v52, v34, v35
	v_max3_f32 v52, v52, v36, v37
	v_max3_f32 v52, v52, v38, v39
	v_max3_f32 v52, v52, v40, v41
	v_max3_f32 v52, v52, v42, v43
	v_max3_f32 v52, v52, v44, v45
	v_max3_f32 v52, v52, v46, v47
	v_max3_f32 v52, v52, v16, v17
	v_max3_f32 v52, v52, v18, v19
	v_max3_f32 v52, v52, v20, v21
	v_max3_f32 v52, v52, v22, v23
	v_max3_f32 v52, v52, v24, v25
	v_max3_f32 v52, v52, v26, v27
	v_max3_f32 v52, v52, v28, v29
	v_max3_f32 v52, v52, v30, v31
	v_mov_b32_e32 v53, v52
	s_nop 1
	v_permlane32_swap_b32_e32 v52, v53
	v_max_f32_e32 v53, v53, v53
	v_max_f32_e32 v52, v52, v52
	v_max_f32_e32 v52, v52, v53
	v_sub_f32_e32 v82, v16, v52
	v_mov_b32_e32 v16, v64
	s_nop 1
	v_permlane32_swap_b32_e32 v64, v16
	v_add_f32_e32 v16, v64, v16
	v_sub_f32_e32 v83, v17, v52
	v_mul_f32_e32 v17, 0x4f800000, v16
	v_cmp_gt_f32_e32 vcc, s65, v16
	v_sub_f32_e32 v84, v18, v52
	v_sub_f32_e32 v85, v19, v52
	v_cndmask_b32_e32 v16, v16, v17, vcc
	v_sqrt_f32_e32 v17, v16
	v_add_f32_e32 v222, 0, v52
	v_sub_f32_e32 v32, v32, v52
	v_sub_f32_e32 v33, v33, v52
	v_add_u32_e32 v18, -1, v17
	v_fma_f32 v19, -v18, v17, v16
	v_cmp_ge_f32_e64 s[0:1], 0, v19
	v_add_u32_e32 v19, 1, v17
	v_sub_f32_e32 v34, v34, v52
	v_cndmask_b32_e64 v18, v17, v18, s[0:1]
	v_fma_f32 v17, -v19, v17, v16
	v_cmp_lt_f32_e64 s[0:1], 0, v17
	v_sub_f32_e32 v35, v35, v52
	v_sub_f32_e32 v36, v36, v52
	v_cndmask_b32_e64 v17, v18, v19, s[0:1]
	v_mul_f32_e32 v18, 0x37800000, v17
	v_cndmask_b32_e32 v17, v17, v18, vcc
	v_cmp_class_f32_e32 vcc, v16, v218
	v_sub_f32_e32 v37, v37, v52
	v_sub_f32_e32 v38, v38, v52
	v_cndmask_b32_e32 v16, v17, v16, vcc
	v_fma_f32 v16, v216, v16, -v222
	v_cmp_ge_f32_e32 vcc, s66, v16
	s_cmp_lg_u64 vcc, exec
	s_cselect_b64 s[0:1], -1, 0
	s_or_b32 s8, s9, s8
	v_sub_f32_e32 v39, v39, v52
	v_sub_f32_e32 v40, v40, v52
	v_sub_f32_e32 v41, v41, v52
	v_sub_f32_e32 v42, v42, v52
	v_sub_f32_e32 v43, v43, v52
	v_sub_f32_e32 v44, v44, v52
	v_sub_f32_e32 v45, v45, v52
	v_sub_f32_e32 v46, v46, v52
	v_sub_f32_e32 v47, v47, v52
	v_xor_b32_e32 v66, 0x80000000, v222
	v_mov_b32_e32 v16, s8
	v_mov_b32_e32 v17, v1
	v_and_b32_e32 v18, 15, v186
	v_mov_b32_e32 v67, v66
	v_mov_b32_e32 v68, v66
	v_mov_b32_e32 v69, v66
	v_mov_b32_e32 v70, v66
	v_mov_b32_e32 v71, v66
	v_mov_b32_e32 v72, v66
	v_mov_b32_e32 v73, v66
	v_mov_b32_e32 v74, v66
	v_mov_b32_e32 v75, v66
	v_mov_b32_e32 v76, v66
	v_mov_b32_e32 v77, v66
	v_mov_b32_e32 v78, v66
	v_mov_b32_e32 v79, v66
	v_mov_b32_e32 v80, v66
	v_mov_b32_e32 v81, v66
	v_exp_f32_e32 v114, v32
	v_exp_f32_e32 v115, v33
	v_exp_f32_e32 v116, v34
	v_exp_f32_e32 v117, v35
	v_exp_f32_e32 v118, v36
	v_exp_f32_e32 v119, v37
	v_exp_f32_e32 v120, v38
	v_exp_f32_e32 v121, v39
	v_exp_f32_e32 v122, v40
	v_exp_f32_e32 v123, v41
	v_exp_f32_e32 v124, v42
	v_exp_f32_e32 v125, v43
	v_exp_f32_e32 v126, v44
	v_exp_f32_e32 v127, v45
	v_exp_f32_e32 v128, v46
	v_exp_f32_e32 v129, v47
	v_mad_i64_i32 v[16:17], s[8:9], v189, s51, v[16:17]
	v_lshlrev_b32_e32 v18, 4, v18
	v_mov_b32_e32 v19, v1
	v_sub_f32_e32 v97, v31, v52
	v_sub_f32_e32 v96, v30, v52
	v_sub_f32_e32 v95, v29, v52
	v_sub_f32_e32 v94, v28, v52
	v_sub_f32_e32 v93, v27, v52
	v_sub_f32_e32 v92, v26, v52
	v_sub_f32_e32 v91, v25, v52
	v_sub_f32_e32 v90, v24, v52
	v_sub_f32_e32 v89, v23, v52
	v_sub_f32_e32 v88, v22, v52
	v_sub_f32_e32 v87, v21, v52
	v_sub_f32_e32 v86, v20, v52
	s_waitcnt vmcnt(0)
; #define SBAR() __builtin_amdgcn_sched_barrier(0)
; #define SLOAD(k0) do { sr_.vs0 = *(const bf16x8*)(&Vh[(long)((k0) + sr) * LDK + sc]); sr_.vs1 = *(const bf16x8*)(&Vh[(long)((k0) + 32 + sr) * LDK + sc]); \
;     sr_.ks0 = *(const bf16x8*)(&Kh[(long)((k0) + sr) * LDK + sc]); sr_.ks1 = *(const bf16x8*)(&Kh[(long)((k0) + 32 + sr) * LDK + sc]); } while (0)
; #define SWRITE(so) do { *(bf16x8*)(lds + (so) + vst0) = sr_.vs0; *(bf16x8*)(lds + (so) + vst1) = sr_.vs1;          \
;     *(bf16x8*)(lds + (so) + kst0) = sr_.ks0; *(bf16x8*)(lds + (so) + kst1) = sr_.ks1; } while (0)
; #define SWAIT() asm volatile("s_waitcnt vmcnt(0)" ::: "memory")
; __device__ __forceinline__ void attn_item(const bf16_t* __restrict__ Qb, const bf16_t* __restrict__ Kh, const bf16_t* __restrict__ Vh, const bf16_t* __restrict__ Zb, ...
;     ...
;   SWAIT(); SWRITE(SLOT); __syncthreads();
;   for (int j = 1; j + 1 < NT; j += 2) {
;     SBAR(); SLOAD((j + 1) * KVBLK); SBAR();
	s_waitcnt vmcnt(3)
	ds_write_b128 v108, v[48:51] offset:32768
	s_waitcnt vmcnt(1)
	ds_write_b128 v109, v[98:101] offset:32768
	ds_write_b128 v112, v[60:63] offset:49152
	s_waitcnt vmcnt(0)
	ds_write_b128 v113, v[102:105] offset:49152
	v_bitop3_b32 v240, v59, v221, v190 bitop3:0xde
	v_lshl_add_u64 v[16:17], v[16:17], 0, v[18:19]
	v_mov_b64_e32 v[64:65], v[14:15]
	v_mov_b64_e32 v[48:49], v[14:15]
	v_mov_b64_e32 v[32:33], v[14:15]
	v_lshl_add_u64 v[214:215], s[20:21], 0, v[16:17]
	v_mov_b64_e32 v[62:63], v[12:13]
	v_mov_b64_e32 v[60:61], v[10:11]
	v_mov_b64_e32 v[58:59], v[8:9]
	v_mov_b64_e32 v[56:57], v[6:7]
	v_mov_b64_e32 v[54:55], v[4:5]
	v_mov_b64_e32 v[52:53], v[2:3]
	v_mov_b64_e32 v[50:51], v[0:1]
	v_mov_b64_e32 v[46:47], v[12:13]
	v_mov_b64_e32 v[44:45], v[10:11]
	v_mov_b64_e32 v[42:43], v[8:9]
	v_mov_b64_e32 v[40:41], v[6:7]
	v_mov_b64_e32 v[38:39], v[4:5]
	v_mov_b64_e32 v[36:37], v[2:3]
	v_mov_b64_e32 v[34:35], v[0:1]
	v_mov_b64_e32 v[30:31], v[12:13]
	v_mov_b64_e32 v[28:29], v[10:11]
	v_mov_b64_e32 v[26:27], v[8:9]
	v_mov_b64_e32 v[24:25], v[6:7]
	v_mov_b64_e32 v[22:23], v[4:5]
	v_mov_b64_e32 v[20:21], v[2:3]
	v_mov_b64_e32 v[18:19], v[0:1]
	v_mov_b64_e32 v[16:17], v[14:15]
	v_mov_b64_e32 v[14:15], v[12:13]
	v_mov_b64_e32 v[12:13], v[10:11]
	v_mov_b64_e32 v[10:11], v[8:9]
	v_mov_b64_e32 v[8:9], v[6:7]
	v_mov_b64_e32 v[6:7], v[4:5]
	v_mov_b64_e32 v[4:5], v[2:3]
	v_mov_b64_e32 v[2:3], v[0:1]
	v_add_co_u32_e32 v248, vcc, s67, v214
	s_nop 1
	v_addc_co_u32_e32 v249, vcc, -1, v215, vcc
	v_add_co_u32_e32 v250, vcc, s68, v214
	s_nop 1
	v_addc_co_u32_e32 v251, vcc, -1, v215, vcc
	global_load_dwordx4 v[180:183], v[248:249], off
	global_load_dwordx4 v[184:187], v[248:249], off offset:-512
	global_load_dwordx4 v[192:195], v[250:251], off
	global_load_dwordx4 v[188:191], v[250:251], off offset:-512
	v_add_u32_e32 v252, 0x10000, v228
	v_add_u32_e32 v253, 0x10000, v229
	v_add_u32_e32 v254, 0x10000, v231
	v_add_u32_e32 v255, 0x10000, v232
	s_waitcnt vmcnt(0)
	ds_write_b128 v252, v[180:183]
	ds_write_b128 v253, v[192:195]
	ds_write_b128 v254, v[184:187] offset:16384
	ds_write_b128 v255, v[188:191] offset:16384
	v_mbcnt_lo_u32_b32 v248, -1, 0
	v_mbcnt_hi_u32_b32 v248, -1, v248
	s_lshr_b32 s79, s33, 6
	s_lshl_b32 s100, s79, 10
	s_lshl_b32 s101, s79, 11
	s_mov_b32 s76, 0x82000
	s_mov_b32 s77, 0
	v_and_b32_e32 v249, 15, v248
	v_lshrrev_b32_e32 v250, 4, v248
	v_lshl_add_u32 v250, s79, 2, v250
	v_and_b32_e32 v251, 15, v250
	v_xor_b32_e32 v251, v249, v251
	v_sub_u32_e32 v251, v251, v249
	v_lshlrev_b32_e32 v251, 4, v251
	v_add_u32_e32 v252, 0xfffbee00, v251
	v_ashrrev_i32_e32 v253, 31, v252
	v_and_b32_e32 v254, 31, v248
	v_lshrrev_b32_e32 v254, 2, v254
	v_lshl_add_u32 v254, s79, 3, v254
	v_sub_u32_e32 v254, v254, v250
	v_add_u32_e32 v254, 0xffffffe0, v254
	v_mov_b32_e32 v255, 0x2080
	v_mul_lo_u32 v254, v254, v255
	v_lshrrev_b32_e32 v255, 5, v248
	v_lshl_add_u32 v254, v255, 6, v254
	v_and_b32_e32 v255, 3, v248
	v_lshl_add_u32 v254, v255, 4, v254
	v_lshlrev_b32_e32 v255, 4, v249
	v_sub_u32_e32 v254, v254, v255
	s_waitcnt lgkmcnt(0)
	v_lshl_add_u64 v[180:181], v[214:215], 0, v[252:253]
	v_ashrrev_i32_e32 v255, 31, v254
	v_add_co_u32_e32 v182, vcc, 0x41000, v180
	s_nop 1
	v_addc_co_u32_e32 v183, vcc, 0, v181, vcc
	v_lshl_add_u64 v[214:215], v[214:215], 0, v[254:255]
	s_mov_b32 s96, 0x8000
	s_mov_b32 s8, 0
	s_cmp_ge_u32 s33, 0x100
	s_cbranch_scc1 .Lh2_pro
	s_barrier
